# hand-written ffn_edge phase (all loads of both items in flight together) and rolling gate loads in the y_a epilogue
# speedup vs baseline: 1.0193x; 1.0105x over previous
;     __device__ __forceinline__ void mid(f32x4 (&acc)[2][2][4][2], const Unit& u, int wr, int wc, int fr, int fq) const {
;         const int row0 = u.pm * BM + wr * 64 + fr, col0 = u.pn * BM + wc * 32 + 8 * fq;
; #pragma unroll
;         for (int ai = 0; ai < 2; ++ai)
; #pragma unroll
;             for (int m = 0; m < 4; ++m) { const bf16_t* prow = P + (size_t)(row0 + ai * HALF + m * 16) * DP;
; #pragma unroll
;                 for (int bj = 0; bj < 2; ++bj) { const int c = col0 + bj * HALF;
;                     float ga[8], gb[8]; unpack8(__builtin_nontemporal_load((const u32x4*)(prow + C_MA + c)), ga); unpack8(*(const u32x4*)(prow + C_MB + c), gb);
; #pragma unroll
;                     for (int e = 0; e < 4; ++e) { acc[ai][bj][m][0][e] *= (1.0f + __expf(-gb[e])) * __builtin_amdgcn_rcpf(1.0f + __expf(-ga[e]));
;                                                   acc[ai][bj][m][1][e] *= (1.0f + __expf(-gb[4 + e])) * __builtin_amdgcn_rcpf(1.0f + __expf(-ga[4 + e])); } }
;                 asm volatile("" ::: "memory"); }
.Lab_mid:
	v_add_u32_e32 v0, s15, v148
	v_mul_lo_u32 v0, v0, s33
	v_lshl_or_b32 v3, s66, 8, v149
	v_lshl_add_u32 v0, v3, 1, v0
	s_add_u32 s68, s8, 0x800
	s_addc_u32 s69, s9, 0
	s_add_u32 s72, s8, 0x2000
	s_addc_u32 s73, s9, 0
	global_load_dwordx4 v[180:183], v0, s[68:69] nt
	global_load_dwordx4 v[232:235], v0, s[72:73]
	global_load_dwordx4 v[184:187], v0, s[68:69] offset:256 nt
	global_load_dwordx4 v[236:239], v0, s[72:73] offset:256
	s_add_u32 s68, s68, 0x28000
	s_addc_u32 s69, s69, 0
	s_add_u32 s72, s72, 0x28000
	s_addc_u32 s73, s73, 0
	global_load_dwordx4 v[188:191], v0, s[68:69] nt
	global_load_dwordx4 v[240:243], v0, s[72:73]
	global_load_dwordx4 v[192:195], v0, s[68:69] offset:256 nt
	global_load_dwordx4 v[244:247], v0, s[72:73] offset:256
	s_add_u32 s68, s68, 0x28000
	s_addc_u32 s69, s69, 0
	s_add_u32 s72, s72, 0x28000
	s_addc_u32 s73, s73, 0
	global_load_dwordx4 v[196:199], v0, s[68:69] nt
	global_load_dwordx4 v[248:251], v0, s[72:73]
	global_load_dwordx4 v[200:203], v0, s[68:69] offset:256 nt
	global_load_dwordx4 v[132:135], v0, s[72:73] offset:256
	s_add_u32 s68, s68, 0x28000
	s_addc_u32 s69, s69, 0
	s_add_u32 s72, s72, 0x28000
	s_addc_u32 s73, s73, 0
	global_load_dwordx4 v[224:227], v0, s[68:69] nt
	global_load_dwordx4 v[136:139], v0, s[72:73]
	global_load_dwordx4 v[228:231], v0, s[68:69] offset:256 nt
	global_load_dwordx4 v[170:173], v0, s[72:73] offset:256
	s_waitcnt vmcnt(14)
	v_lshlrev_b32_e32 v174, 16, v180
	v_lshlrev_b32_e32 v175, 16, v181
	v_lshlrev_b32_e32 v176, 16, v182
	v_lshlrev_b32_e32 v177, 16, v183
	v_and_b32_e32 v180, 0xffff0000, v180
	v_and_b32_e32 v181, 0xffff0000, v181
	v_and_b32_e32 v182, 0xffff0000, v182
	v_and_b32_e32 v183, 0xffff0000, v183
	v_lshlrev_b32_e32 v205, 16, v232
	v_lshlrev_b32_e32 v206, 16, v233
	v_lshlrev_b32_e32 v208, 16, v234
	v_lshlrev_b32_e32 v210, 16, v235
	v_and_b32_e32 v232, 0xffff0000, v232
	v_and_b32_e32 v233, 0xffff0000, v233
	v_and_b32_e32 v234, 0xffff0000, v234
	v_and_b32_e32 v235, 0xffff0000, v235
	v_mul_f32_e32 v174, 0xbfb8aa3b, v174
	v_mul_f32_e32 v180, 0xbfb8aa3b, v180
	v_mul_f32_e32 v175, 0xbfb8aa3b, v175
	v_mul_f32_e32 v181, 0xbfb8aa3b, v181
	v_mul_f32_e32 v176, 0xbfb8aa3b, v176
	v_mul_f32_e32 v182, 0xbfb8aa3b, v182
	v_mul_f32_e32 v177, 0xbfb8aa3b, v177
	v_mul_f32_e32 v183, 0xbfb8aa3b, v183
	v_mul_f32_e32 v205, 0xbfb8aa3b, v205
	v_mul_f32_e32 v232, 0xbfb8aa3b, v232
	v_mul_f32_e32 v206, 0xbfb8aa3b, v206
	v_mul_f32_e32 v233, 0xbfb8aa3b, v233
	v_mul_f32_e32 v208, 0xbfb8aa3b, v208
	v_mul_f32_e32 v234, 0xbfb8aa3b, v234
	v_mul_f32_e32 v210, 0xbfb8aa3b, v210
	v_mul_f32_e32 v235, 0xbfb8aa3b, v235
	v_exp_f32_e32 v174, v174
	v_exp_f32_e32 v180, v180
	v_exp_f32_e32 v175, v175
	v_exp_f32_e32 v181, v181
	v_exp_f32_e32 v176, v176
	v_exp_f32_e32 v182, v182
	v_exp_f32_e32 v177, v177
	v_exp_f32_e32 v183, v183
	v_exp_f32_e32 v205, v205
	v_exp_f32_e32 v232, v232
	v_exp_f32_e32 v206, v206
	v_exp_f32_e32 v233, v233
	v_exp_f32_e32 v208, v208
	v_exp_f32_e32 v234, v234
	v_exp_f32_e32 v210, v210
	v_exp_f32_e32 v235, v235
	v_add_f32_e32 v174, 1.0, v174
	v_add_f32_e32 v180, 1.0, v180
	v_add_f32_e32 v175, 1.0, v175
	v_add_f32_e32 v181, 1.0, v181
	v_add_f32_e32 v176, 1.0, v176
	v_add_f32_e32 v182, 1.0, v182
	v_add_f32_e32 v177, 1.0, v177
	v_add_f32_e32 v183, 1.0, v183
	v_add_f32_e32 v205, 1.0, v205
	v_add_f32_e32 v232, 1.0, v232
	v_add_f32_e32 v206, 1.0, v206
	v_add_f32_e32 v233, 1.0, v233
	v_add_f32_e32 v208, 1.0, v208
	v_add_f32_e32 v234, 1.0, v234
	v_add_f32_e32 v210, 1.0, v210
	v_add_f32_e32 v235, 1.0, v235
	v_rcp_f32_e32 v174, v174
	v_rcp_f32_e32 v180, v180
	v_rcp_f32_e32 v175, v175
	v_rcp_f32_e32 v181, v181
	v_rcp_f32_e32 v176, v176
	v_rcp_f32_e32 v182, v182
	v_rcp_f32_e32 v177, v177
	v_rcp_f32_e32 v183, v183
	v_mul_f32_e32 v205, v205, v174
	v_mul_f32_e32 v232, v232, v180
	v_mul_f32_e32 v206, v206, v175
	v_mul_f32_e32 v233, v233, v181
	v_mul_f32_e32 v208, v208, v176
	v_mul_f32_e32 v234, v234, v182
	v_mul_f32_e32 v210, v210, v177
	v_mul_f32_e32 v235, v235, v183
	v_mul_f32_e32 v128, v128, v205
	v_mul_f32_e32 v129, v129, v232
	v_mul_f32_e32 v130, v130, v206
	v_mul_f32_e32 v131, v131, v233
	v_mul_f32_e32 v124, v124, v208
	v_mul_f32_e32 v125, v125, v234
	v_mul_f32_e32 v126, v126, v210
	v_mul_f32_e32 v127, v127, v235
	s_add_u32 s68, s68, 0xc8000
	s_addc_u32 s69, s69, 0
	s_add_u32 s72, s72, 0xc8000
	s_addc_u32 s73, s73, 0
	global_load_dwordx4 v[180:183], v0, s[68:69] nt
	global_load_dwordx4 v[232:235], v0, s[72:73]
	s_waitcnt vmcnt(14)
;     __device__ __forceinline__ void mid(f32x4 (&acc)[2][2][4][2], const Unit& u, int wr, int wc, int fr, int fq) const {
;         const int row0 = u.pm * BM + wr * 64 + fr, col0 = u.pn * BM + wc * 32 + 8 * fq;
; #pragma unroll
;         for (int ai = 0; ai < 2; ++ai)
; #pragma unroll
;             for (int m = 0; m < 4; ++m) { const bf16_t* prow = P + (size_t)(row0 + ai * HALF + m * 16) * DP;
; #pragma unroll
;                 for (int bj = 0; bj < 2; ++bj) { const int c = col0 + bj * HALF;
;                     float ga[8], gb[8]; unpack8(__builtin_nontemporal_load((const u32x4*)(prow + C_MA + c)), ga); unpack8(*(const u32x4*)(prow + C_MB + c), gb);
; #pragma unroll
;                     for (int e = 0; e < 4; ++e) { acc[ai][bj][m][0][e] *= (1.0f + __expf(-gb[e])) * __builtin_amdgcn_rcpf(1.0f + __expf(-ga[e]));
;                                                   acc[ai][bj][m][1][e] *= (1.0f + __expf(-gb[4 + e])) * __builtin_amdgcn_rcpf(1.0f + __expf(-ga[4 + e])); } }
;                 asm volatile("" ::: "memory"); }
	v_lshlrev_b32_e32 v174, 16, v184
	v_lshlrev_b32_e32 v175, 16, v185
	v_lshlrev_b32_e32 v176, 16, v186
	v_lshlrev_b32_e32 v177, 16, v187
	v_and_b32_e32 v184, 0xffff0000, v184
	v_and_b32_e32 v185, 0xffff0000, v185
	v_and_b32_e32 v186, 0xffff0000, v186
	v_and_b32_e32 v187, 0xffff0000, v187
	v_lshlrev_b32_e32 v205, 16, v236
	v_lshlrev_b32_e32 v206, 16, v237
	v_lshlrev_b32_e32 v208, 16, v238
	v_lshlrev_b32_e32 v210, 16, v239
	v_and_b32_e32 v236, 0xffff0000, v236
	v_and_b32_e32 v237, 0xffff0000, v237
	v_and_b32_e32 v238, 0xffff0000, v238
	v_and_b32_e32 v239, 0xffff0000, v239
	v_mul_f32_e32 v174, 0xbfb8aa3b, v174
	v_mul_f32_e32 v184, 0xbfb8aa3b, v184
	v_mul_f32_e32 v175, 0xbfb8aa3b, v175
	v_mul_f32_e32 v185, 0xbfb8aa3b, v185
	v_mul_f32_e32 v176, 0xbfb8aa3b, v176
	v_mul_f32_e32 v186, 0xbfb8aa3b, v186
	v_mul_f32_e32 v177, 0xbfb8aa3b, v177
	v_mul_f32_e32 v187, 0xbfb8aa3b, v187
	v_mul_f32_e32 v205, 0xbfb8aa3b, v205
	v_mul_f32_e32 v236, 0xbfb8aa3b, v236
	v_mul_f32_e32 v206, 0xbfb8aa3b, v206
	v_mul_f32_e32 v237, 0xbfb8aa3b, v237
	v_mul_f32_e32 v208, 0xbfb8aa3b, v208
	v_mul_f32_e32 v238, 0xbfb8aa3b, v238
	v_mul_f32_e32 v210, 0xbfb8aa3b, v210
	v_mul_f32_e32 v239, 0xbfb8aa3b, v239
	v_exp_f32_e32 v174, v174
	v_exp_f32_e32 v184, v184
	v_exp_f32_e32 v175, v175
	v_exp_f32_e32 v185, v185
	v_exp_f32_e32 v176, v176
	v_exp_f32_e32 v186, v186
	v_exp_f32_e32 v177, v177
	v_exp_f32_e32 v187, v187
	v_exp_f32_e32 v205, v205
	v_exp_f32_e32 v236, v236
	v_exp_f32_e32 v206, v206
	v_exp_f32_e32 v237, v237
	v_exp_f32_e32 v208, v208
	v_exp_f32_e32 v238, v238
	v_exp_f32_e32 v210, v210
	v_exp_f32_e32 v239, v239
	v_add_f32_e32 v174, 1.0, v174
	v_add_f32_e32 v184, 1.0, v184
	v_add_f32_e32 v175, 1.0, v175
	v_add_f32_e32 v185, 1.0, v185
	v_add_f32_e32 v176, 1.0, v176
	v_add_f32_e32 v186, 1.0, v186
	v_add_f32_e32 v177, 1.0, v177
	v_add_f32_e32 v187, 1.0, v187
	v_add_f32_e32 v205, 1.0, v205
	v_add_f32_e32 v236, 1.0, v236
	v_add_f32_e32 v206, 1.0, v206
	v_add_f32_e32 v237, 1.0, v237
	v_add_f32_e32 v208, 1.0, v208
	v_add_f32_e32 v238, 1.0, v238
	v_add_f32_e32 v210, 1.0, v210
	v_add_f32_e32 v239, 1.0, v239
	v_rcp_f32_e32 v174, v174
	v_rcp_f32_e32 v184, v184
	v_rcp_f32_e32 v175, v175
	v_rcp_f32_e32 v185, v185
	v_rcp_f32_e32 v176, v176
	v_rcp_f32_e32 v186, v186
	v_rcp_f32_e32 v177, v177
	v_rcp_f32_e32 v187, v187
	v_mul_f32_e32 v205, v205, v174
	v_mul_f32_e32 v236, v236, v184
	v_mul_f32_e32 v206, v206, v175
	v_mul_f32_e32 v237, v237, v185
	v_mul_f32_e32 v208, v208, v176
	v_mul_f32_e32 v238, v238, v186
	v_mul_f32_e32 v210, v210, v177
	v_mul_f32_e32 v239, v239, v187
	v_mul_f32_e32 v96, v96, v205
	v_mul_f32_e32 v97, v97, v236
	v_mul_f32_e32 v98, v98, v206
	v_mul_f32_e32 v99, v99, v237
	v_mul_f32_e32 v92, v92, v208
	v_mul_f32_e32 v93, v93, v238
	v_mul_f32_e32 v94, v94, v210
	v_mul_f32_e32 v95, v95, v239
	global_load_dwordx4 v[184:187], v0, s[68:69] offset:256 nt
	global_load_dwordx4 v[236:239], v0, s[72:73] offset:256
	s_waitcnt vmcnt(14)
	v_lshlrev_b32_e32 v174, 16, v188
	v_lshlrev_b32_e32 v175, 16, v189
	v_lshlrev_b32_e32 v176, 16, v190
	v_lshlrev_b32_e32 v177, 16, v191
	v_and_b32_e32 v188, 0xffff0000, v188
	v_and_b32_e32 v189, 0xffff0000, v189
	v_and_b32_e32 v190, 0xffff0000, v190
	v_and_b32_e32 v191, 0xffff0000, v191
	v_lshlrev_b32_e32 v205, 16, v240
	v_lshlrev_b32_e32 v206, 16, v241
	v_lshlrev_b32_e32 v208, 16, v242
	v_lshlrev_b32_e32 v210, 16, v243
	v_and_b32_e32 v240, 0xffff0000, v240
	v_and_b32_e32 v241, 0xffff0000, v241
	v_and_b32_e32 v242, 0xffff0000, v242
	v_and_b32_e32 v243, 0xffff0000, v243
	v_mul_f32_e32 v174, 0xbfb8aa3b, v174
	v_mul_f32_e32 v188, 0xbfb8aa3b, v188
	v_mul_f32_e32 v175, 0xbfb8aa3b, v175
	v_mul_f32_e32 v189, 0xbfb8aa3b, v189
	v_mul_f32_e32 v176, 0xbfb8aa3b, v176
	v_mul_f32_e32 v190, 0xbfb8aa3b, v190
	v_mul_f32_e32 v177, 0xbfb8aa3b, v177
	v_mul_f32_e32 v191, 0xbfb8aa3b, v191
	v_mul_f32_e32 v205, 0xbfb8aa3b, v205
	v_mul_f32_e32 v240, 0xbfb8aa3b, v240
	v_mul_f32_e32 v206, 0xbfb8aa3b, v206
	v_mul_f32_e32 v241, 0xbfb8aa3b, v241
	v_mul_f32_e32 v208, 0xbfb8aa3b, v208
	v_mul_f32_e32 v242, 0xbfb8aa3b, v242
	v_mul_f32_e32 v210, 0xbfb8aa3b, v210
	v_mul_f32_e32 v243, 0xbfb8aa3b, v243
	v_exp_f32_e32 v174, v174
	v_exp_f32_e32 v188, v188
	v_exp_f32_e32 v175, v175
	v_exp_f32_e32 v189, v189
	v_exp_f32_e32 v176, v176
	v_exp_f32_e32 v190, v190
	v_exp_f32_e32 v177, v177
	v_exp_f32_e32 v191, v191
	v_exp_f32_e32 v205, v205
	v_exp_f32_e32 v240, v240
	v_exp_f32_e32 v206, v206
	v_exp_f32_e32 v241, v241
	v_exp_f32_e32 v208, v208
	v_exp_f32_e32 v242, v242
	v_exp_f32_e32 v210, v210
	v_exp_f32_e32 v243, v243
	v_add_f32_e32 v174, 1.0, v174
	v_add_f32_e32 v188, 1.0, v188
	v_add_f32_e32 v175, 1.0, v175
	v_add_f32_e32 v189, 1.0, v189
	v_add_f32_e32 v176, 1.0, v176
	v_add_f32_e32 v190, 1.0, v190
	v_add_f32_e32 v177, 1.0, v177
	v_add_f32_e32 v191, 1.0, v191
	v_add_f32_e32 v205, 1.0, v205
	v_add_f32_e32 v240, 1.0, v240
	v_add_f32_e32 v206, 1.0, v206
	v_add_f32_e32 v241, 1.0, v241
	v_add_f32_e32 v208, 1.0, v208
	v_add_f32_e32 v242, 1.0, v242
	v_add_f32_e32 v210, 1.0, v210
	v_add_f32_e32 v243, 1.0, v243
	v_rcp_f32_e32 v174, v174
	v_rcp_f32_e32 v188, v188
	v_rcp_f32_e32 v175, v175
	v_rcp_f32_e32 v189, v189
	v_rcp_f32_e32 v176, v176
	v_rcp_f32_e32 v190, v190
	v_rcp_f32_e32 v177, v177
	v_rcp_f32_e32 v191, v191
	v_mul_f32_e32 v205, v205, v174
	v_mul_f32_e32 v240, v240, v188
	v_mul_f32_e32 v206, v206, v175
	v_mul_f32_e32 v241, v241, v189
	v_mul_f32_e32 v208, v208, v176
	v_mul_f32_e32 v242, v242, v190
	v_mul_f32_e32 v210, v210, v177
	v_mul_f32_e32 v243, v243, v191
	v_mul_f32_e32 v120, v120, v205
	v_mul_f32_e32 v121, v121, v240
	v_mul_f32_e32 v122, v122, v206
	v_mul_f32_e32 v123, v123, v241
	v_mul_f32_e32 v116, v116, v208
	v_mul_f32_e32 v117, v117, v242
	v_mul_f32_e32 v118, v118, v210
	v_mul_f32_e32 v119, v119, v243
	s_add_u32 s68, s68, 0x28000
	s_addc_u32 s69, s69, 0
	s_add_u32 s72, s72, 0x28000
	s_addc_u32 s73, s73, 0
	global_load_dwordx4 v[188:191], v0, s[68:69] nt
	global_load_dwordx4 v[240:243], v0, s[72:73]
	s_waitcnt vmcnt(14)
;     __device__ __forceinline__ void mid(f32x4 (&acc)[2][2][4][2], const Unit& u, int wr, int wc, int fr, int fq) const {
;         const int row0 = u.pm * BM + wr * 64 + fr, col0 = u.pn * BM + wc * 32 + 8 * fq;
; #pragma unroll
;         for (int ai = 0; ai < 2; ++ai)
; #pragma unroll
;             for (int m = 0; m < 4; ++m) { const bf16_t* prow = P + (size_t)(row0 + ai * HALF + m * 16) * DP;
; #pragma unroll
;                 for (int bj = 0; bj < 2; ++bj) { const int c = col0 + bj * HALF;
;                     float ga[8], gb[8]; unpack8(__builtin_nontemporal_load((const u32x4*)(prow + C_MA + c)), ga); unpack8(*(const u32x4*)(prow + C_MB + c), gb);
; #pragma unroll
;                     for (int e = 0; e < 4; ++e) { acc[ai][bj][m][0][e] *= (1.0f + __expf(-gb[e])) * __builtin_amdgcn_rcpf(1.0f + __expf(-ga[e]));
;                                                   acc[ai][bj][m][1][e] *= (1.0f + __expf(-gb[4 + e])) * __builtin_amdgcn_rcpf(1.0f + __expf(-ga[4 + e])); } }
;                 asm volatile("" ::: "memory"); }
	v_lshlrev_b32_e32 v174, 16, v192
	v_lshlrev_b32_e32 v175, 16, v193
	v_lshlrev_b32_e32 v176, 16, v194
	v_lshlrev_b32_e32 v177, 16, v195
	v_and_b32_e32 v192, 0xffff0000, v192
	v_and_b32_e32 v193, 0xffff0000, v193
	v_and_b32_e32 v194, 0xffff0000, v194
	v_and_b32_e32 v195, 0xffff0000, v195
	v_lshlrev_b32_e32 v205, 16, v244
	v_lshlrev_b32_e32 v206, 16, v245
	v_lshlrev_b32_e32 v208, 16, v246
	v_lshlrev_b32_e32 v210, 16, v247
	v_and_b32_e32 v244, 0xffff0000, v244
	v_and_b32_e32 v245, 0xffff0000, v245
	v_and_b32_e32 v246, 0xffff0000, v246
	v_and_b32_e32 v247, 0xffff0000, v247
	v_mul_f32_e32 v174, 0xbfb8aa3b, v174
	v_mul_f32_e32 v192, 0xbfb8aa3b, v192
	v_mul_f32_e32 v175, 0xbfb8aa3b, v175
	v_mul_f32_e32 v193, 0xbfb8aa3b, v193
	v_mul_f32_e32 v176, 0xbfb8aa3b, v176
	v_mul_f32_e32 v194, 0xbfb8aa3b, v194
	v_mul_f32_e32 v177, 0xbfb8aa3b, v177
	v_mul_f32_e32 v195, 0xbfb8aa3b, v195
	v_mul_f32_e32 v205, 0xbfb8aa3b, v205
	v_mul_f32_e32 v244, 0xbfb8aa3b, v244
	v_mul_f32_e32 v206, 0xbfb8aa3b, v206
	v_mul_f32_e32 v245, 0xbfb8aa3b, v245
	v_mul_f32_e32 v208, 0xbfb8aa3b, v208
	v_mul_f32_e32 v246, 0xbfb8aa3b, v246
	v_mul_f32_e32 v210, 0xbfb8aa3b, v210
	v_mul_f32_e32 v247, 0xbfb8aa3b, v247
	v_exp_f32_e32 v174, v174
	v_exp_f32_e32 v192, v192
	v_exp_f32_e32 v175, v175
	v_exp_f32_e32 v193, v193
	v_exp_f32_e32 v176, v176
	v_exp_f32_e32 v194, v194
	v_exp_f32_e32 v177, v177
	v_exp_f32_e32 v195, v195
	v_exp_f32_e32 v205, v205
	v_exp_f32_e32 v244, v244
	v_exp_f32_e32 v206, v206
	v_exp_f32_e32 v245, v245
	v_exp_f32_e32 v208, v208
	v_exp_f32_e32 v246, v246
	v_exp_f32_e32 v210, v210
	v_exp_f32_e32 v247, v247
	v_add_f32_e32 v174, 1.0, v174
	v_add_f32_e32 v192, 1.0, v192
	v_add_f32_e32 v175, 1.0, v175
	v_add_f32_e32 v193, 1.0, v193
	v_add_f32_e32 v176, 1.0, v176
	v_add_f32_e32 v194, 1.0, v194
	v_add_f32_e32 v177, 1.0, v177
	v_add_f32_e32 v195, 1.0, v195
	v_add_f32_e32 v205, 1.0, v205
	v_add_f32_e32 v244, 1.0, v244
	v_add_f32_e32 v206, 1.0, v206
	v_add_f32_e32 v245, 1.0, v245
	v_add_f32_e32 v208, 1.0, v208
	v_add_f32_e32 v246, 1.0, v246
	v_add_f32_e32 v210, 1.0, v210
	v_add_f32_e32 v247, 1.0, v247
	v_rcp_f32_e32 v174, v174
	v_rcp_f32_e32 v192, v192
	v_rcp_f32_e32 v175, v175
	v_rcp_f32_e32 v193, v193
	v_rcp_f32_e32 v176, v176
	v_rcp_f32_e32 v194, v194
	v_rcp_f32_e32 v177, v177
	v_rcp_f32_e32 v195, v195
	v_mul_f32_e32 v205, v205, v174
	v_mul_f32_e32 v244, v244, v192
	v_mul_f32_e32 v206, v206, v175
	v_mul_f32_e32 v245, v245, v193
	v_mul_f32_e32 v208, v208, v176
	v_mul_f32_e32 v246, v246, v194
	v_mul_f32_e32 v210, v210, v177
	v_mul_f32_e32 v247, v247, v195
	v_mul_f32_e32 v88, v88, v205
	v_mul_f32_e32 v89, v89, v244
	v_mul_f32_e32 v90, v90, v206
	v_mul_f32_e32 v91, v91, v245
	v_mul_f32_e32 v84, v84, v208
	v_mul_f32_e32 v85, v85, v246
	v_mul_f32_e32 v86, v86, v210
	v_mul_f32_e32 v87, v87, v247
	global_load_dwordx4 v[192:195], v0, s[68:69] offset:256 nt
	global_load_dwordx4 v[244:247], v0, s[72:73] offset:256
	s_waitcnt vmcnt(14)
	v_lshlrev_b32_e32 v174, 16, v196
	v_lshlrev_b32_e32 v175, 16, v197
	v_lshlrev_b32_e32 v176, 16, v198
	v_lshlrev_b32_e32 v177, 16, v199
	v_and_b32_e32 v196, 0xffff0000, v196
	v_and_b32_e32 v197, 0xffff0000, v197
	v_and_b32_e32 v198, 0xffff0000, v198
	v_and_b32_e32 v199, 0xffff0000, v199
	v_lshlrev_b32_e32 v205, 16, v248
	v_lshlrev_b32_e32 v206, 16, v249
	v_lshlrev_b32_e32 v208, 16, v250
	v_lshlrev_b32_e32 v210, 16, v251
	v_and_b32_e32 v248, 0xffff0000, v248
	v_and_b32_e32 v249, 0xffff0000, v249
	v_and_b32_e32 v250, 0xffff0000, v250
	v_and_b32_e32 v251, 0xffff0000, v251
	v_mul_f32_e32 v174, 0xbfb8aa3b, v174
	v_mul_f32_e32 v196, 0xbfb8aa3b, v196
	v_mul_f32_e32 v175, 0xbfb8aa3b, v175
	v_mul_f32_e32 v197, 0xbfb8aa3b, v197
	v_mul_f32_e32 v176, 0xbfb8aa3b, v176
	v_mul_f32_e32 v198, 0xbfb8aa3b, v198
	v_mul_f32_e32 v177, 0xbfb8aa3b, v177
	v_mul_f32_e32 v199, 0xbfb8aa3b, v199
	v_mul_f32_e32 v205, 0xbfb8aa3b, v205
	v_mul_f32_e32 v248, 0xbfb8aa3b, v248
	v_mul_f32_e32 v206, 0xbfb8aa3b, v206
	v_mul_f32_e32 v249, 0xbfb8aa3b, v249
	v_mul_f32_e32 v208, 0xbfb8aa3b, v208
	v_mul_f32_e32 v250, 0xbfb8aa3b, v250
	v_mul_f32_e32 v210, 0xbfb8aa3b, v210
	v_mul_f32_e32 v251, 0xbfb8aa3b, v251
	v_exp_f32_e32 v174, v174
	v_exp_f32_e32 v196, v196
	v_exp_f32_e32 v175, v175
	v_exp_f32_e32 v197, v197
	v_exp_f32_e32 v176, v176
	v_exp_f32_e32 v198, v198
	v_exp_f32_e32 v177, v177
	v_exp_f32_e32 v199, v199
	v_exp_f32_e32 v205, v205
	v_exp_f32_e32 v248, v248
	v_exp_f32_e32 v206, v206
	v_exp_f32_e32 v249, v249
	v_exp_f32_e32 v208, v208
	v_exp_f32_e32 v250, v250
	v_exp_f32_e32 v210, v210
	v_exp_f32_e32 v251, v251
	v_add_f32_e32 v174, 1.0, v174
	v_add_f32_e32 v196, 1.0, v196
	v_add_f32_e32 v175, 1.0, v175
	v_add_f32_e32 v197, 1.0, v197
	v_add_f32_e32 v176, 1.0, v176
	v_add_f32_e32 v198, 1.0, v198
	v_add_f32_e32 v177, 1.0, v177
	v_add_f32_e32 v199, 1.0, v199
	v_add_f32_e32 v205, 1.0, v205
	v_add_f32_e32 v248, 1.0, v248
	v_add_f32_e32 v206, 1.0, v206
	v_add_f32_e32 v249, 1.0, v249
	v_add_f32_e32 v208, 1.0, v208
	v_add_f32_e32 v250, 1.0, v250
	v_add_f32_e32 v210, 1.0, v210
	v_add_f32_e32 v251, 1.0, v251
	v_rcp_f32_e32 v174, v174
	v_rcp_f32_e32 v196, v196
	v_rcp_f32_e32 v175, v175
	v_rcp_f32_e32 v197, v197
	v_rcp_f32_e32 v176, v176
	v_rcp_f32_e32 v198, v198
	v_rcp_f32_e32 v177, v177
	v_rcp_f32_e32 v199, v199
	v_mul_f32_e32 v205, v205, v174
	v_mul_f32_e32 v248, v248, v196
	v_mul_f32_e32 v206, v206, v175
	v_mul_f32_e32 v249, v249, v197
	v_mul_f32_e32 v208, v208, v176
	v_mul_f32_e32 v250, v250, v198
	v_mul_f32_e32 v210, v210, v177
	v_mul_f32_e32 v251, v251, v199
	v_mul_f32_e32 v112, v112, v205
	v_mul_f32_e32 v113, v113, v248
	v_mul_f32_e32 v114, v114, v206
	v_mul_f32_e32 v115, v115, v249
	v_mul_f32_e32 v108, v108, v208
	v_mul_f32_e32 v109, v109, v250
	v_mul_f32_e32 v110, v110, v210
	v_mul_f32_e32 v111, v111, v251
	s_add_u32 s68, s68, 0x28000
	s_addc_u32 s69, s69, 0
	s_add_u32 s72, s72, 0x28000
	s_addc_u32 s73, s73, 0
	global_load_dwordx4 v[196:199], v0, s[68:69] nt
	global_load_dwordx4 v[248:251], v0, s[72:73]
	s_waitcnt vmcnt(14)
;     __device__ __forceinline__ void mid(f32x4 (&acc)[2][2][4][2], const Unit& u, int wr, int wc, int fr, int fq) const {
;         const int row0 = u.pm * BM + wr * 64 + fr, col0 = u.pn * BM + wc * 32 + 8 * fq;
; #pragma unroll
;         for (int ai = 0; ai < 2; ++ai)
; #pragma unroll
;             for (int m = 0; m < 4; ++m) { const bf16_t* prow = P + (size_t)(row0 + ai * HALF + m * 16) * DP;
; #pragma unroll
;                 for (int bj = 0; bj < 2; ++bj) { const int c = col0 + bj * HALF;
;                     float ga[8], gb[8]; unpack8(__builtin_nontemporal_load((const u32x4*)(prow + C_MA + c)), ga); unpack8(*(const u32x4*)(prow + C_MB + c), gb);
; #pragma unroll
;                     for (int e = 0; e < 4; ++e) { acc[ai][bj][m][0][e] *= (1.0f + __expf(-gb[e])) * __builtin_amdgcn_rcpf(1.0f + __expf(-ga[e]));
;                                                   acc[ai][bj][m][1][e] *= (1.0f + __expf(-gb[4 + e])) * __builtin_amdgcn_rcpf(1.0f + __expf(-ga[4 + e])); } }
;                 asm volatile("" ::: "memory"); }
	v_lshlrev_b32_e32 v174, 16, v200
	v_lshlrev_b32_e32 v175, 16, v201
	v_lshlrev_b32_e32 v176, 16, v202
	v_lshlrev_b32_e32 v177, 16, v203
	v_and_b32_e32 v200, 0xffff0000, v200
	v_and_b32_e32 v201, 0xffff0000, v201
	v_and_b32_e32 v202, 0xffff0000, v202
	v_and_b32_e32 v203, 0xffff0000, v203
	v_lshlrev_b32_e32 v205, 16, v132
	v_lshlrev_b32_e32 v206, 16, v133
	v_lshlrev_b32_e32 v208, 16, v134
	v_lshlrev_b32_e32 v210, 16, v135
	v_and_b32_e32 v132, 0xffff0000, v132
	v_and_b32_e32 v133, 0xffff0000, v133
	v_and_b32_e32 v134, 0xffff0000, v134
	v_and_b32_e32 v135, 0xffff0000, v135
	v_mul_f32_e32 v174, 0xbfb8aa3b, v174
	v_mul_f32_e32 v200, 0xbfb8aa3b, v200
	v_mul_f32_e32 v175, 0xbfb8aa3b, v175
	v_mul_f32_e32 v201, 0xbfb8aa3b, v201
	v_mul_f32_e32 v176, 0xbfb8aa3b, v176
	v_mul_f32_e32 v202, 0xbfb8aa3b, v202
	v_mul_f32_e32 v177, 0xbfb8aa3b, v177
	v_mul_f32_e32 v203, 0xbfb8aa3b, v203
	v_mul_f32_e32 v205, 0xbfb8aa3b, v205
	v_mul_f32_e32 v132, 0xbfb8aa3b, v132
	v_mul_f32_e32 v206, 0xbfb8aa3b, v206
	v_mul_f32_e32 v133, 0xbfb8aa3b, v133
	v_mul_f32_e32 v208, 0xbfb8aa3b, v208
	v_mul_f32_e32 v134, 0xbfb8aa3b, v134
	v_mul_f32_e32 v210, 0xbfb8aa3b, v210
	v_mul_f32_e32 v135, 0xbfb8aa3b, v135
	v_exp_f32_e32 v174, v174
	v_exp_f32_e32 v200, v200
	v_exp_f32_e32 v175, v175
	v_exp_f32_e32 v201, v201
	v_exp_f32_e32 v176, v176
	v_exp_f32_e32 v202, v202
	v_exp_f32_e32 v177, v177
	v_exp_f32_e32 v203, v203
	v_exp_f32_e32 v205, v205
	v_exp_f32_e32 v132, v132
	v_exp_f32_e32 v206, v206
	v_exp_f32_e32 v133, v133
	v_exp_f32_e32 v208, v208
	v_exp_f32_e32 v134, v134
	v_exp_f32_e32 v210, v210
	v_exp_f32_e32 v135, v135
	v_add_f32_e32 v174, 1.0, v174
	v_add_f32_e32 v200, 1.0, v200
	v_add_f32_e32 v175, 1.0, v175
	v_add_f32_e32 v201, 1.0, v201
	v_add_f32_e32 v176, 1.0, v176
	v_add_f32_e32 v202, 1.0, v202
	v_add_f32_e32 v177, 1.0, v177
	v_add_f32_e32 v203, 1.0, v203
	v_add_f32_e32 v205, 1.0, v205
	v_add_f32_e32 v132, 1.0, v132
	v_add_f32_e32 v206, 1.0, v206
	v_add_f32_e32 v133, 1.0, v133
	v_add_f32_e32 v208, 1.0, v208
	v_add_f32_e32 v134, 1.0, v134
	v_add_f32_e32 v210, 1.0, v210
	v_add_f32_e32 v135, 1.0, v135
	v_rcp_f32_e32 v174, v174
	v_rcp_f32_e32 v200, v200
	v_rcp_f32_e32 v175, v175
	v_rcp_f32_e32 v201, v201
	v_rcp_f32_e32 v176, v176
	v_rcp_f32_e32 v202, v202
	v_rcp_f32_e32 v177, v177
	v_rcp_f32_e32 v203, v203
	v_mul_f32_e32 v205, v205, v174
	v_mul_f32_e32 v132, v132, v200
	v_mul_f32_e32 v206, v206, v175
	v_mul_f32_e32 v133, v133, v201
	v_mul_f32_e32 v208, v208, v176
	v_mul_f32_e32 v134, v134, v202
	v_mul_f32_e32 v210, v210, v177
	v_mul_f32_e32 v135, v135, v203
	v_mul_f32_e32 v80, v80, v205
	v_mul_f32_e32 v81, v81, v132
	v_mul_f32_e32 v82, v82, v206
	v_mul_f32_e32 v83, v83, v133
	v_mul_f32_e32 v76, v76, v208
	v_mul_f32_e32 v77, v77, v134
	v_mul_f32_e32 v78, v78, v210
	v_mul_f32_e32 v79, v79, v135
	global_load_dwordx4 v[200:203], v0, s[68:69] offset:256 nt
	global_load_dwordx4 v[132:135], v0, s[72:73] offset:256
	s_waitcnt vmcnt(14)
	v_lshlrev_b32_e32 v174, 16, v224
	v_lshlrev_b32_e32 v175, 16, v225
	v_lshlrev_b32_e32 v176, 16, v226
	v_lshlrev_b32_e32 v177, 16, v227
	v_and_b32_e32 v224, 0xffff0000, v224
	v_and_b32_e32 v225, 0xffff0000, v225
	v_and_b32_e32 v226, 0xffff0000, v226
	v_and_b32_e32 v227, 0xffff0000, v227
	v_lshlrev_b32_e32 v205, 16, v136
	v_lshlrev_b32_e32 v206, 16, v137
	v_lshlrev_b32_e32 v208, 16, v138
	v_lshlrev_b32_e32 v210, 16, v139
	v_and_b32_e32 v136, 0xffff0000, v136
	v_and_b32_e32 v137, 0xffff0000, v137
	v_and_b32_e32 v138, 0xffff0000, v138
	v_and_b32_e32 v139, 0xffff0000, v139
	v_mul_f32_e32 v174, 0xbfb8aa3b, v174
	v_mul_f32_e32 v224, 0xbfb8aa3b, v224
	v_mul_f32_e32 v175, 0xbfb8aa3b, v175
	v_mul_f32_e32 v225, 0xbfb8aa3b, v225
	v_mul_f32_e32 v176, 0xbfb8aa3b, v176
	v_mul_f32_e32 v226, 0xbfb8aa3b, v226
	v_mul_f32_e32 v177, 0xbfb8aa3b, v177
	v_mul_f32_e32 v227, 0xbfb8aa3b, v227
	v_mul_f32_e32 v205, 0xbfb8aa3b, v205
	v_mul_f32_e32 v136, 0xbfb8aa3b, v136
	v_mul_f32_e32 v206, 0xbfb8aa3b, v206
	v_mul_f32_e32 v137, 0xbfb8aa3b, v137
	v_mul_f32_e32 v208, 0xbfb8aa3b, v208
	v_mul_f32_e32 v138, 0xbfb8aa3b, v138
	v_mul_f32_e32 v210, 0xbfb8aa3b, v210
	v_mul_f32_e32 v139, 0xbfb8aa3b, v139
	v_exp_f32_e32 v174, v174
	v_exp_f32_e32 v224, v224
	v_exp_f32_e32 v175, v175
	v_exp_f32_e32 v225, v225
	v_exp_f32_e32 v176, v176
	v_exp_f32_e32 v226, v226
	v_exp_f32_e32 v177, v177
	v_exp_f32_e32 v227, v227
	v_exp_f32_e32 v205, v205
	v_exp_f32_e32 v136, v136
	v_exp_f32_e32 v206, v206
	v_exp_f32_e32 v137, v137
	v_exp_f32_e32 v208, v208
	v_exp_f32_e32 v138, v138
	v_exp_f32_e32 v210, v210
	v_exp_f32_e32 v139, v139
	v_add_f32_e32 v174, 1.0, v174
	v_add_f32_e32 v224, 1.0, v224
	v_add_f32_e32 v175, 1.0, v175
	v_add_f32_e32 v225, 1.0, v225
	v_add_f32_e32 v176, 1.0, v176
	v_add_f32_e32 v226, 1.0, v226
	v_add_f32_e32 v177, 1.0, v177
	v_add_f32_e32 v227, 1.0, v227
	v_add_f32_e32 v205, 1.0, v205
	v_add_f32_e32 v136, 1.0, v136
	v_add_f32_e32 v206, 1.0, v206
	v_add_f32_e32 v137, 1.0, v137
	v_add_f32_e32 v208, 1.0, v208
	v_add_f32_e32 v138, 1.0, v138
	v_add_f32_e32 v210, 1.0, v210
	v_add_f32_e32 v139, 1.0, v139
	v_rcp_f32_e32 v174, v174
	v_rcp_f32_e32 v224, v224
	v_rcp_f32_e32 v175, v175
	v_rcp_f32_e32 v225, v225
	v_rcp_f32_e32 v176, v176
	v_rcp_f32_e32 v226, v226
	v_rcp_f32_e32 v177, v177
	v_rcp_f32_e32 v227, v227
	v_mul_f32_e32 v205, v205, v174
	v_mul_f32_e32 v136, v136, v224
	v_mul_f32_e32 v206, v206, v175
	v_mul_f32_e32 v137, v137, v225
	v_mul_f32_e32 v208, v208, v176
	v_mul_f32_e32 v138, v138, v226
	v_mul_f32_e32 v210, v210, v177
	v_mul_f32_e32 v139, v139, v227
	v_mul_f32_e32 v104, v104, v205
	v_mul_f32_e32 v105, v105, v136
	v_mul_f32_e32 v106, v106, v206
	v_mul_f32_e32 v107, v107, v137
	v_mul_f32_e32 v100, v100, v208
	v_mul_f32_e32 v101, v101, v138
	v_mul_f32_e32 v102, v102, v210
	v_mul_f32_e32 v103, v103, v139
	s_add_u32 s68, s68, 0x28000
	s_addc_u32 s69, s69, 0
	s_add_u32 s72, s72, 0x28000
	s_addc_u32 s73, s73, 0
	global_load_dwordx4 v[224:227], v0, s[68:69] nt
	global_load_dwordx4 v[136:139], v0, s[72:73]
	s_waitcnt vmcnt(14)
;     __device__ __forceinline__ void mid(f32x4 (&acc)[2][2][4][2], const Unit& u, int wr, int wc, int fr, int fq) const {
;         const int row0 = u.pm * BM + wr * 64 + fr, col0 = u.pn * BM + wc * 32 + 8 * fq;
; #pragma unroll
;         for (int ai = 0; ai < 2; ++ai)
; #pragma unroll
;             for (int m = 0; m < 4; ++m) { const bf16_t* prow = P + (size_t)(row0 + ai * HALF + m * 16) * DP;
; #pragma unroll
;                 for (int bj = 0; bj < 2; ++bj) { const int c = col0 + bj * HALF;
;                     float ga[8], gb[8]; unpack8(__builtin_nontemporal_load((const u32x4*)(prow + C_MA + c)), ga); unpack8(*(const u32x4*)(prow + C_MB + c), gb);
; #pragma unroll
;                     for (int e = 0; e < 4; ++e) { acc[ai][bj][m][0][e] *= (1.0f + __expf(-gb[e])) * __builtin_amdgcn_rcpf(1.0f + __expf(-ga[e]));
;                                                   acc[ai][bj][m][1][e] *= (1.0f + __expf(-gb[4 + e])) * __builtin_amdgcn_rcpf(1.0f + __expf(-ga[4 + e])); } }
;                 asm volatile("" ::: "memory"); }
	v_lshlrev_b32_e32 v174, 16, v228
	v_lshlrev_b32_e32 v175, 16, v229
	v_lshlrev_b32_e32 v176, 16, v230
	v_lshlrev_b32_e32 v177, 16, v231
	v_and_b32_e32 v228, 0xffff0000, v228
	v_and_b32_e32 v229, 0xffff0000, v229
	v_and_b32_e32 v230, 0xffff0000, v230
	v_and_b32_e32 v231, 0xffff0000, v231
	v_lshlrev_b32_e32 v205, 16, v170
	v_lshlrev_b32_e32 v206, 16, v171
	v_lshlrev_b32_e32 v208, 16, v172
	v_lshlrev_b32_e32 v210, 16, v173
	v_and_b32_e32 v170, 0xffff0000, v170
	v_and_b32_e32 v171, 0xffff0000, v171
	v_and_b32_e32 v172, 0xffff0000, v172
	v_and_b32_e32 v173, 0xffff0000, v173
	v_mul_f32_e32 v174, 0xbfb8aa3b, v174
	v_mul_f32_e32 v228, 0xbfb8aa3b, v228
	v_mul_f32_e32 v175, 0xbfb8aa3b, v175
	v_mul_f32_e32 v229, 0xbfb8aa3b, v229
	v_mul_f32_e32 v176, 0xbfb8aa3b, v176
	v_mul_f32_e32 v230, 0xbfb8aa3b, v230
	v_mul_f32_e32 v177, 0xbfb8aa3b, v177
	v_mul_f32_e32 v231, 0xbfb8aa3b, v231
	v_mul_f32_e32 v205, 0xbfb8aa3b, v205
	v_mul_f32_e32 v170, 0xbfb8aa3b, v170
	v_mul_f32_e32 v206, 0xbfb8aa3b, v206
	v_mul_f32_e32 v171, 0xbfb8aa3b, v171
	v_mul_f32_e32 v208, 0xbfb8aa3b, v208
	v_mul_f32_e32 v172, 0xbfb8aa3b, v172
	v_mul_f32_e32 v210, 0xbfb8aa3b, v210
	v_mul_f32_e32 v173, 0xbfb8aa3b, v173
	v_exp_f32_e32 v174, v174
	v_exp_f32_e32 v228, v228
	v_exp_f32_e32 v175, v175
	v_exp_f32_e32 v229, v229
	v_exp_f32_e32 v176, v176
	v_exp_f32_e32 v230, v230
	v_exp_f32_e32 v177, v177
	v_exp_f32_e32 v231, v231
	v_exp_f32_e32 v205, v205
	v_exp_f32_e32 v170, v170
	v_exp_f32_e32 v206, v206
	v_exp_f32_e32 v171, v171
	v_exp_f32_e32 v208, v208
	v_exp_f32_e32 v172, v172
	v_exp_f32_e32 v210, v210
	v_exp_f32_e32 v173, v173
	v_add_f32_e32 v174, 1.0, v174
	v_add_f32_e32 v228, 1.0, v228
	v_add_f32_e32 v175, 1.0, v175
	v_add_f32_e32 v229, 1.0, v229
	v_add_f32_e32 v176, 1.0, v176
	v_add_f32_e32 v230, 1.0, v230
	v_add_f32_e32 v177, 1.0, v177
	v_add_f32_e32 v231, 1.0, v231
	v_add_f32_e32 v205, 1.0, v205
	v_add_f32_e32 v170, 1.0, v170
	v_add_f32_e32 v206, 1.0, v206
	v_add_f32_e32 v171, 1.0, v171
	v_add_f32_e32 v208, 1.0, v208
	v_add_f32_e32 v172, 1.0, v172
	v_add_f32_e32 v210, 1.0, v210
	v_add_f32_e32 v173, 1.0, v173
	v_rcp_f32_e32 v174, v174
	v_rcp_f32_e32 v228, v228
	v_rcp_f32_e32 v175, v175
	v_rcp_f32_e32 v229, v229
	v_rcp_f32_e32 v176, v176
	v_rcp_f32_e32 v230, v230
	v_rcp_f32_e32 v177, v177
	v_rcp_f32_e32 v231, v231
	v_mul_f32_e32 v205, v205, v174
	v_mul_f32_e32 v170, v170, v228
	v_mul_f32_e32 v206, v206, v175
	v_mul_f32_e32 v171, v171, v229
	v_mul_f32_e32 v208, v208, v176
	v_mul_f32_e32 v172, v172, v230
	v_mul_f32_e32 v210, v210, v177
	v_mul_f32_e32 v173, v173, v231
	v_mul_f32_e32 v72, v72, v205
	v_mul_f32_e32 v73, v73, v170
	v_mul_f32_e32 v74, v74, v206
	v_mul_f32_e32 v75, v75, v171
	v_mul_f32_e32 v68, v68, v208
	v_mul_f32_e32 v69, v69, v172
	v_mul_f32_e32 v70, v70, v210
	v_mul_f32_e32 v71, v71, v173
	global_load_dwordx4 v[228:231], v0, s[68:69] offset:256 nt
	global_load_dwordx4 v[170:173], v0, s[72:73] offset:256
	s_waitcnt vmcnt(14)
	v_lshlrev_b32_e32 v174, 16, v180
	v_lshlrev_b32_e32 v175, 16, v181
	v_lshlrev_b32_e32 v176, 16, v182
	v_lshlrev_b32_e32 v177, 16, v183
	v_and_b32_e32 v180, 0xffff0000, v180
	v_and_b32_e32 v181, 0xffff0000, v181
	v_and_b32_e32 v182, 0xffff0000, v182
	v_and_b32_e32 v183, 0xffff0000, v183
	v_lshlrev_b32_e32 v205, 16, v232
	v_lshlrev_b32_e32 v206, 16, v233
	v_lshlrev_b32_e32 v208, 16, v234
	v_lshlrev_b32_e32 v210, 16, v235
	v_and_b32_e32 v232, 0xffff0000, v232
	v_and_b32_e32 v233, 0xffff0000, v233
	v_and_b32_e32 v234, 0xffff0000, v234
	v_and_b32_e32 v235, 0xffff0000, v235
	v_mul_f32_e32 v174, 0xbfb8aa3b, v174
	v_mul_f32_e32 v180, 0xbfb8aa3b, v180
	v_mul_f32_e32 v175, 0xbfb8aa3b, v175
	v_mul_f32_e32 v181, 0xbfb8aa3b, v181
	v_mul_f32_e32 v176, 0xbfb8aa3b, v176
	v_mul_f32_e32 v182, 0xbfb8aa3b, v182
	v_mul_f32_e32 v177, 0xbfb8aa3b, v177
	v_mul_f32_e32 v183, 0xbfb8aa3b, v183
	v_mul_f32_e32 v205, 0xbfb8aa3b, v205
	v_mul_f32_e32 v232, 0xbfb8aa3b, v232
	v_mul_f32_e32 v206, 0xbfb8aa3b, v206
	v_mul_f32_e32 v233, 0xbfb8aa3b, v233
	v_mul_f32_e32 v208, 0xbfb8aa3b, v208
	v_mul_f32_e32 v234, 0xbfb8aa3b, v234
	v_mul_f32_e32 v210, 0xbfb8aa3b, v210
	v_mul_f32_e32 v235, 0xbfb8aa3b, v235
	v_exp_f32_e32 v174, v174
	v_exp_f32_e32 v180, v180
	v_exp_f32_e32 v175, v175
	v_exp_f32_e32 v181, v181
	v_exp_f32_e32 v176, v176
	v_exp_f32_e32 v182, v182
	v_exp_f32_e32 v177, v177
	v_exp_f32_e32 v183, v183
	v_exp_f32_e32 v205, v205
	v_exp_f32_e32 v232, v232
	v_exp_f32_e32 v206, v206
	v_exp_f32_e32 v233, v233
	v_exp_f32_e32 v208, v208
	v_exp_f32_e32 v234, v234
	v_exp_f32_e32 v210, v210
	v_exp_f32_e32 v235, v235
	v_add_f32_e32 v174, 1.0, v174
	v_add_f32_e32 v180, 1.0, v180
	v_add_f32_e32 v175, 1.0, v175
	v_add_f32_e32 v181, 1.0, v181
	v_add_f32_e32 v176, 1.0, v176
	v_add_f32_e32 v182, 1.0, v182
	v_add_f32_e32 v177, 1.0, v177
	v_add_f32_e32 v183, 1.0, v183
	v_add_f32_e32 v205, 1.0, v205
	v_add_f32_e32 v232, 1.0, v232
	v_add_f32_e32 v206, 1.0, v206
	v_add_f32_e32 v233, 1.0, v233
	v_add_f32_e32 v208, 1.0, v208
	v_add_f32_e32 v234, 1.0, v234
	v_add_f32_e32 v210, 1.0, v210
	v_add_f32_e32 v235, 1.0, v235
	v_rcp_f32_e32 v174, v174
	v_rcp_f32_e32 v180, v180
	v_rcp_f32_e32 v175, v175
	v_rcp_f32_e32 v181, v181
	v_rcp_f32_e32 v176, v176
	v_rcp_f32_e32 v182, v182
	v_rcp_f32_e32 v177, v177
	v_rcp_f32_e32 v183, v183
	v_mul_f32_e32 v205, v205, v174
	v_mul_f32_e32 v232, v232, v180
	v_mul_f32_e32 v206, v206, v175
	v_mul_f32_e32 v233, v233, v181
	v_mul_f32_e32 v208, v208, v176
	v_mul_f32_e32 v234, v234, v182
	v_mul_f32_e32 v210, v210, v177
	v_mul_f32_e32 v235, v235, v183
	v_mul_f32_e32 v64, v64, v205
	v_mul_f32_e32 v65, v65, v232
	v_mul_f32_e32 v66, v66, v206
	v_mul_f32_e32 v67, v67, v233
	v_mul_f32_e32 v60, v60, v208
	v_mul_f32_e32 v61, v61, v234
	v_mul_f32_e32 v62, v62, v210
	v_mul_f32_e32 v63, v63, v235
	s_waitcnt vmcnt(12)
;     __device__ __forceinline__ void mid(f32x4 (&acc)[2][2][4][2], const Unit& u, int wr, int wc, int fr, int fq) const {
;         const int row0 = u.pm * BM + wr * 64 + fr, col0 = u.pn * BM + wc * 32 + 8 * fq;
; #pragma unroll
;         for (int ai = 0; ai < 2; ++ai)
; #pragma unroll
;             for (int m = 0; m < 4; ++m) { const bf16_t* prow = P + (size_t)(row0 + ai * HALF + m * 16) * DP;
; #pragma unroll
;                 for (int bj = 0; bj < 2; ++bj) { const int c = col0 + bj * HALF;
;                     float ga[8], gb[8]; unpack8(__builtin_nontemporal_load((const u32x4*)(prow + C_MA + c)), ga); unpack8(*(const u32x4*)(prow + C_MB + c), gb);
; #pragma unroll
;                     for (int e = 0; e < 4; ++e) { acc[ai][bj][m][0][e] *= (1.0f + __expf(-gb[e])) * __builtin_amdgcn_rcpf(1.0f + __expf(-ga[e]));
;                                                   acc[ai][bj][m][1][e] *= (1.0f + __expf(-gb[4 + e])) * __builtin_amdgcn_rcpf(1.0f + __expf(-ga[4 + e])); } }
;                 asm volatile("" ::: "memory"); }
	v_lshlrev_b32_e32 v174, 16, v184
	v_lshlrev_b32_e32 v175, 16, v185
	v_lshlrev_b32_e32 v176, 16, v186
	v_lshlrev_b32_e32 v177, 16, v187
	v_and_b32_e32 v184, 0xffff0000, v184
	v_and_b32_e32 v185, 0xffff0000, v185
	v_and_b32_e32 v186, 0xffff0000, v186
	v_and_b32_e32 v187, 0xffff0000, v187
	v_lshlrev_b32_e32 v205, 16, v236
	v_lshlrev_b32_e32 v206, 16, v237
	v_lshlrev_b32_e32 v208, 16, v238
	v_lshlrev_b32_e32 v210, 16, v239
	v_and_b32_e32 v236, 0xffff0000, v236
	v_and_b32_e32 v237, 0xffff0000, v237
	v_and_b32_e32 v238, 0xffff0000, v238
	v_and_b32_e32 v239, 0xffff0000, v239
	v_mul_f32_e32 v174, 0xbfb8aa3b, v174
	v_mul_f32_e32 v184, 0xbfb8aa3b, v184
	v_mul_f32_e32 v175, 0xbfb8aa3b, v175
	v_mul_f32_e32 v185, 0xbfb8aa3b, v185
	v_mul_f32_e32 v176, 0xbfb8aa3b, v176
	v_mul_f32_e32 v186, 0xbfb8aa3b, v186
	v_mul_f32_e32 v177, 0xbfb8aa3b, v177
	v_mul_f32_e32 v187, 0xbfb8aa3b, v187
	v_mul_f32_e32 v205, 0xbfb8aa3b, v205
	v_mul_f32_e32 v236, 0xbfb8aa3b, v236
	v_mul_f32_e32 v206, 0xbfb8aa3b, v206
	v_mul_f32_e32 v237, 0xbfb8aa3b, v237
	v_mul_f32_e32 v208, 0xbfb8aa3b, v208
	v_mul_f32_e32 v238, 0xbfb8aa3b, v238
	v_mul_f32_e32 v210, 0xbfb8aa3b, v210
	v_mul_f32_e32 v239, 0xbfb8aa3b, v239
	v_exp_f32_e32 v174, v174
	v_exp_f32_e32 v184, v184
	v_exp_f32_e32 v175, v175
	v_exp_f32_e32 v185, v185
	v_exp_f32_e32 v176, v176
	v_exp_f32_e32 v186, v186
	v_exp_f32_e32 v177, v177
	v_exp_f32_e32 v187, v187
	v_exp_f32_e32 v205, v205
	v_exp_f32_e32 v236, v236
	v_exp_f32_e32 v206, v206
	v_exp_f32_e32 v237, v237
	v_exp_f32_e32 v208, v208
	v_exp_f32_e32 v238, v238
	v_exp_f32_e32 v210, v210
	v_exp_f32_e32 v239, v239
	v_add_f32_e32 v174, 1.0, v174
	v_add_f32_e32 v184, 1.0, v184
	v_add_f32_e32 v175, 1.0, v175
	v_add_f32_e32 v185, 1.0, v185
	v_add_f32_e32 v176, 1.0, v176
	v_add_f32_e32 v186, 1.0, v186
	v_add_f32_e32 v177, 1.0, v177
	v_add_f32_e32 v187, 1.0, v187
	v_add_f32_e32 v205, 1.0, v205
	v_add_f32_e32 v236, 1.0, v236
	v_add_f32_e32 v206, 1.0, v206
	v_add_f32_e32 v237, 1.0, v237
	v_add_f32_e32 v208, 1.0, v208
	v_add_f32_e32 v238, 1.0, v238
	v_add_f32_e32 v210, 1.0, v210
	v_add_f32_e32 v239, 1.0, v239
	v_rcp_f32_e32 v174, v174
	v_rcp_f32_e32 v184, v184
	v_rcp_f32_e32 v175, v175
	v_rcp_f32_e32 v185, v185
	v_rcp_f32_e32 v176, v176
	v_rcp_f32_e32 v186, v186
	v_rcp_f32_e32 v177, v177
	v_rcp_f32_e32 v187, v187
	v_mul_f32_e32 v205, v205, v174
	v_mul_f32_e32 v236, v236, v184
	v_mul_f32_e32 v206, v206, v175
	v_mul_f32_e32 v237, v237, v185
	v_mul_f32_e32 v208, v208, v176
	v_mul_f32_e32 v238, v238, v186
	v_mul_f32_e32 v210, v210, v177
	v_mul_f32_e32 v239, v239, v187
	v_mul_f32_e32 v32, v32, v205
	v_mul_f32_e32 v33, v33, v236
	v_mul_f32_e32 v34, v34, v206
	v_mul_f32_e32 v35, v35, v237
	v_mul_f32_e32 v28, v28, v208
	v_mul_f32_e32 v29, v29, v238
	v_mul_f32_e32 v30, v30, v210
	v_mul_f32_e32 v31, v31, v239
	s_waitcnt vmcnt(10)
	v_lshlrev_b32_e32 v174, 16, v188
	v_lshlrev_b32_e32 v175, 16, v189
	v_lshlrev_b32_e32 v176, 16, v190
	v_lshlrev_b32_e32 v177, 16, v191
	v_and_b32_e32 v188, 0xffff0000, v188
	v_and_b32_e32 v189, 0xffff0000, v189
	v_and_b32_e32 v190, 0xffff0000, v190
	v_and_b32_e32 v191, 0xffff0000, v191
	v_lshlrev_b32_e32 v205, 16, v240
	v_lshlrev_b32_e32 v206, 16, v241
	v_lshlrev_b32_e32 v208, 16, v242
	v_lshlrev_b32_e32 v210, 16, v243
	v_and_b32_e32 v240, 0xffff0000, v240
	v_and_b32_e32 v241, 0xffff0000, v241
	v_and_b32_e32 v242, 0xffff0000, v242
	v_and_b32_e32 v243, 0xffff0000, v243
	v_mul_f32_e32 v174, 0xbfb8aa3b, v174
	v_mul_f32_e32 v188, 0xbfb8aa3b, v188
	v_mul_f32_e32 v175, 0xbfb8aa3b, v175
	v_mul_f32_e32 v189, 0xbfb8aa3b, v189
	v_mul_f32_e32 v176, 0xbfb8aa3b, v176
	v_mul_f32_e32 v190, 0xbfb8aa3b, v190
	v_mul_f32_e32 v177, 0xbfb8aa3b, v177
	v_mul_f32_e32 v191, 0xbfb8aa3b, v191
	v_mul_f32_e32 v205, 0xbfb8aa3b, v205
	v_mul_f32_e32 v240, 0xbfb8aa3b, v240
	v_mul_f32_e32 v206, 0xbfb8aa3b, v206
	v_mul_f32_e32 v241, 0xbfb8aa3b, v241
	v_mul_f32_e32 v208, 0xbfb8aa3b, v208
	v_mul_f32_e32 v242, 0xbfb8aa3b, v242
	v_mul_f32_e32 v210, 0xbfb8aa3b, v210
	v_mul_f32_e32 v243, 0xbfb8aa3b, v243
	v_exp_f32_e32 v174, v174
	v_exp_f32_e32 v188, v188
	v_exp_f32_e32 v175, v175
	v_exp_f32_e32 v189, v189
	v_exp_f32_e32 v176, v176
	v_exp_f32_e32 v190, v190
	v_exp_f32_e32 v177, v177
	v_exp_f32_e32 v191, v191
	v_exp_f32_e32 v205, v205
	v_exp_f32_e32 v240, v240
	v_exp_f32_e32 v206, v206
	v_exp_f32_e32 v241, v241
	v_exp_f32_e32 v208, v208
	v_exp_f32_e32 v242, v242
	v_exp_f32_e32 v210, v210
	v_exp_f32_e32 v243, v243
	v_add_f32_e32 v174, 1.0, v174
	v_add_f32_e32 v188, 1.0, v188
	v_add_f32_e32 v175, 1.0, v175
	v_add_f32_e32 v189, 1.0, v189
	v_add_f32_e32 v176, 1.0, v176
	v_add_f32_e32 v190, 1.0, v190
	v_add_f32_e32 v177, 1.0, v177
	v_add_f32_e32 v191, 1.0, v191
	v_add_f32_e32 v205, 1.0, v205
	v_add_f32_e32 v240, 1.0, v240
	v_add_f32_e32 v206, 1.0, v206
	v_add_f32_e32 v241, 1.0, v241
	v_add_f32_e32 v208, 1.0, v208
	v_add_f32_e32 v242, 1.0, v242
	v_add_f32_e32 v210, 1.0, v210
	v_add_f32_e32 v243, 1.0, v243
	v_rcp_f32_e32 v174, v174
	v_rcp_f32_e32 v188, v188
	v_rcp_f32_e32 v175, v175
	v_rcp_f32_e32 v189, v189
	v_rcp_f32_e32 v176, v176
	v_rcp_f32_e32 v190, v190
	v_rcp_f32_e32 v177, v177
	v_rcp_f32_e32 v191, v191
	v_mul_f32_e32 v205, v205, v174
	v_mul_f32_e32 v240, v240, v188
	v_mul_f32_e32 v206, v206, v175
	v_mul_f32_e32 v241, v241, v189
	v_mul_f32_e32 v208, v208, v176
	v_mul_f32_e32 v242, v242, v190
	v_mul_f32_e32 v210, v210, v177
	v_mul_f32_e32 v243, v243, v191
	v_mul_f32_e32 v56, v56, v205
	v_mul_f32_e32 v57, v57, v240
	v_mul_f32_e32 v58, v58, v206
	v_mul_f32_e32 v59, v59, v241
	v_mul_f32_e32 v52, v52, v208
	v_mul_f32_e32 v53, v53, v242
	v_mul_f32_e32 v54, v54, v210
	v_mul_f32_e32 v55, v55, v243
	s_waitcnt vmcnt(8)
;     __device__ __forceinline__ void mid(f32x4 (&acc)[2][2][4][2], const Unit& u, int wr, int wc, int fr, int fq) const {
;         const int row0 = u.pm * BM + wr * 64 + fr, col0 = u.pn * BM + wc * 32 + 8 * fq;
; #pragma unroll
;         for (int ai = 0; ai < 2; ++ai)
; #pragma unroll
;             for (int m = 0; m < 4; ++m) { const bf16_t* prow = P + (size_t)(row0 + ai * HALF + m * 16) * DP;
; #pragma unroll
;                 for (int bj = 0; bj < 2; ++bj) { const int c = col0 + bj * HALF;
;                     float ga[8], gb[8]; unpack8(__builtin_nontemporal_load((const u32x4*)(prow + C_MA + c)), ga); unpack8(*(const u32x4*)(prow + C_MB + c), gb);
; #pragma unroll
;                     for (int e = 0; e < 4; ++e) { acc[ai][bj][m][0][e] *= (1.0f + __expf(-gb[e])) * __builtin_amdgcn_rcpf(1.0f + __expf(-ga[e]));
;                                                   acc[ai][bj][m][1][e] *= (1.0f + __expf(-gb[4 + e])) * __builtin_amdgcn_rcpf(1.0f + __expf(-ga[4 + e])); } }
;                 asm volatile("" ::: "memory"); }
	v_lshlrev_b32_e32 v174, 16, v192
	v_lshlrev_b32_e32 v175, 16, v193
	v_lshlrev_b32_e32 v176, 16, v194
	v_lshlrev_b32_e32 v177, 16, v195
	v_and_b32_e32 v192, 0xffff0000, v192
	v_and_b32_e32 v193, 0xffff0000, v193
	v_and_b32_e32 v194, 0xffff0000, v194
	v_and_b32_e32 v195, 0xffff0000, v195
	v_lshlrev_b32_e32 v205, 16, v244
	v_lshlrev_b32_e32 v206, 16, v245
	v_lshlrev_b32_e32 v208, 16, v246
	v_lshlrev_b32_e32 v210, 16, v247
	v_and_b32_e32 v244, 0xffff0000, v244
	v_and_b32_e32 v245, 0xffff0000, v245
	v_and_b32_e32 v246, 0xffff0000, v246
	v_and_b32_e32 v247, 0xffff0000, v247
	v_mul_f32_e32 v174, 0xbfb8aa3b, v174
	v_mul_f32_e32 v192, 0xbfb8aa3b, v192
	v_mul_f32_e32 v175, 0xbfb8aa3b, v175
	v_mul_f32_e32 v193, 0xbfb8aa3b, v193
	v_mul_f32_e32 v176, 0xbfb8aa3b, v176
	v_mul_f32_e32 v194, 0xbfb8aa3b, v194
	v_mul_f32_e32 v177, 0xbfb8aa3b, v177
	v_mul_f32_e32 v195, 0xbfb8aa3b, v195
	v_mul_f32_e32 v205, 0xbfb8aa3b, v205
	v_mul_f32_e32 v244, 0xbfb8aa3b, v244
	v_mul_f32_e32 v206, 0xbfb8aa3b, v206
	v_mul_f32_e32 v245, 0xbfb8aa3b, v245
	v_mul_f32_e32 v208, 0xbfb8aa3b, v208
	v_mul_f32_e32 v246, 0xbfb8aa3b, v246
	v_mul_f32_e32 v210, 0xbfb8aa3b, v210
	v_mul_f32_e32 v247, 0xbfb8aa3b, v247
	v_exp_f32_e32 v174, v174
	v_exp_f32_e32 v192, v192
	v_exp_f32_e32 v175, v175
	v_exp_f32_e32 v193, v193
	v_exp_f32_e32 v176, v176
	v_exp_f32_e32 v194, v194
	v_exp_f32_e32 v177, v177
	v_exp_f32_e32 v195, v195
	v_exp_f32_e32 v205, v205
	v_exp_f32_e32 v244, v244
	v_exp_f32_e32 v206, v206
	v_exp_f32_e32 v245, v245
	v_exp_f32_e32 v208, v208
	v_exp_f32_e32 v246, v246
	v_exp_f32_e32 v210, v210
	v_exp_f32_e32 v247, v247
	v_add_f32_e32 v174, 1.0, v174
	v_add_f32_e32 v192, 1.0, v192
	v_add_f32_e32 v175, 1.0, v175
	v_add_f32_e32 v193, 1.0, v193
	v_add_f32_e32 v176, 1.0, v176
	v_add_f32_e32 v194, 1.0, v194
	v_add_f32_e32 v177, 1.0, v177
	v_add_f32_e32 v195, 1.0, v195
	v_add_f32_e32 v205, 1.0, v205
	v_add_f32_e32 v244, 1.0, v244
	v_add_f32_e32 v206, 1.0, v206
	v_add_f32_e32 v245, 1.0, v245
	v_add_f32_e32 v208, 1.0, v208
	v_add_f32_e32 v246, 1.0, v246
	v_add_f32_e32 v210, 1.0, v210
	v_add_f32_e32 v247, 1.0, v247
	v_rcp_f32_e32 v174, v174
	v_rcp_f32_e32 v192, v192
	v_rcp_f32_e32 v175, v175
	v_rcp_f32_e32 v193, v193
	v_rcp_f32_e32 v176, v176
	v_rcp_f32_e32 v194, v194
	v_rcp_f32_e32 v177, v177
	v_rcp_f32_e32 v195, v195
	v_mul_f32_e32 v205, v205, v174
	v_mul_f32_e32 v244, v244, v192
	v_mul_f32_e32 v206, v206, v175
	v_mul_f32_e32 v245, v245, v193
	v_mul_f32_e32 v208, v208, v176
	v_mul_f32_e32 v246, v246, v194
	v_mul_f32_e32 v210, v210, v177
	v_mul_f32_e32 v247, v247, v195
	v_mul_f32_e32 v24, v24, v205
	v_mul_f32_e32 v25, v25, v244
	v_mul_f32_e32 v26, v26, v206
	v_mul_f32_e32 v27, v27, v245
	v_mul_f32_e32 v20, v20, v208
	v_mul_f32_e32 v21, v21, v246
	v_mul_f32_e32 v22, v22, v210
	v_mul_f32_e32 v23, v23, v247
	s_waitcnt vmcnt(6)
	v_lshlrev_b32_e32 v174, 16, v196
	v_lshlrev_b32_e32 v175, 16, v197
	v_lshlrev_b32_e32 v176, 16, v198
	v_lshlrev_b32_e32 v177, 16, v199
	v_and_b32_e32 v196, 0xffff0000, v196
	v_and_b32_e32 v197, 0xffff0000, v197
	v_and_b32_e32 v198, 0xffff0000, v198
	v_and_b32_e32 v199, 0xffff0000, v199
	v_lshlrev_b32_e32 v205, 16, v248
	v_lshlrev_b32_e32 v206, 16, v249
	v_lshlrev_b32_e32 v208, 16, v250
	v_lshlrev_b32_e32 v210, 16, v251
	v_and_b32_e32 v248, 0xffff0000, v248
	v_and_b32_e32 v249, 0xffff0000, v249
	v_and_b32_e32 v250, 0xffff0000, v250
	v_and_b32_e32 v251, 0xffff0000, v251
	v_mul_f32_e32 v174, 0xbfb8aa3b, v174
	v_mul_f32_e32 v196, 0xbfb8aa3b, v196
	v_mul_f32_e32 v175, 0xbfb8aa3b, v175
	v_mul_f32_e32 v197, 0xbfb8aa3b, v197
	v_mul_f32_e32 v176, 0xbfb8aa3b, v176
	v_mul_f32_e32 v198, 0xbfb8aa3b, v198
	v_mul_f32_e32 v177, 0xbfb8aa3b, v177
	v_mul_f32_e32 v199, 0xbfb8aa3b, v199
	v_mul_f32_e32 v205, 0xbfb8aa3b, v205
	v_mul_f32_e32 v248, 0xbfb8aa3b, v248
	v_mul_f32_e32 v206, 0xbfb8aa3b, v206
	v_mul_f32_e32 v249, 0xbfb8aa3b, v249
	v_mul_f32_e32 v208, 0xbfb8aa3b, v208
	v_mul_f32_e32 v250, 0xbfb8aa3b, v250
	v_mul_f32_e32 v210, 0xbfb8aa3b, v210
	v_mul_f32_e32 v251, 0xbfb8aa3b, v251
	v_exp_f32_e32 v174, v174
	v_exp_f32_e32 v196, v196
	v_exp_f32_e32 v175, v175
	v_exp_f32_e32 v197, v197
	v_exp_f32_e32 v176, v176
	v_exp_f32_e32 v198, v198
	v_exp_f32_e32 v177, v177
	v_exp_f32_e32 v199, v199
	v_exp_f32_e32 v205, v205
	v_exp_f32_e32 v248, v248
	v_exp_f32_e32 v206, v206
	v_exp_f32_e32 v249, v249
	v_exp_f32_e32 v208, v208
	v_exp_f32_e32 v250, v250
	v_exp_f32_e32 v210, v210
	v_exp_f32_e32 v251, v251
	v_add_f32_e32 v174, 1.0, v174
	v_add_f32_e32 v196, 1.0, v196
	v_add_f32_e32 v175, 1.0, v175
	v_add_f32_e32 v197, 1.0, v197
	v_add_f32_e32 v176, 1.0, v176
	v_add_f32_e32 v198, 1.0, v198
	v_add_f32_e32 v177, 1.0, v177
	v_add_f32_e32 v199, 1.0, v199
	v_add_f32_e32 v205, 1.0, v205
	v_add_f32_e32 v248, 1.0, v248
	v_add_f32_e32 v206, 1.0, v206
	v_add_f32_e32 v249, 1.0, v249
	v_add_f32_e32 v208, 1.0, v208
	v_add_f32_e32 v250, 1.0, v250
	v_add_f32_e32 v210, 1.0, v210
	v_add_f32_e32 v251, 1.0, v251
	v_rcp_f32_e32 v174, v174
	v_rcp_f32_e32 v196, v196
	v_rcp_f32_e32 v175, v175
	v_rcp_f32_e32 v197, v197
	v_rcp_f32_e32 v176, v176
	v_rcp_f32_e32 v198, v198
	v_rcp_f32_e32 v177, v177
	v_rcp_f32_e32 v199, v199
	v_mul_f32_e32 v205, v205, v174
	v_mul_f32_e32 v248, v248, v196
	v_mul_f32_e32 v206, v206, v175
	v_mul_f32_e32 v249, v249, v197
	v_mul_f32_e32 v208, v208, v176
	v_mul_f32_e32 v250, v250, v198
	v_mul_f32_e32 v210, v210, v177
	v_mul_f32_e32 v251, v251, v199
	v_mul_f32_e32 v48, v48, v205
	v_mul_f32_e32 v49, v49, v248
	v_mul_f32_e32 v50, v50, v206
	v_mul_f32_e32 v51, v51, v249
	v_mul_f32_e32 v44, v44, v208
	v_mul_f32_e32 v45, v45, v250
	v_mul_f32_e32 v46, v46, v210
	v_mul_f32_e32 v47, v47, v251
	s_waitcnt vmcnt(4)
;     __device__ __forceinline__ void mid(f32x4 (&acc)[2][2][4][2], const Unit& u, int wr, int wc, int fr, int fq) const {
;         const int row0 = u.pm * BM + wr * 64 + fr, col0 = u.pn * BM + wc * 32 + 8 * fq;
; #pragma unroll
;         for (int ai = 0; ai < 2; ++ai)
; #pragma unroll
;             for (int m = 0; m < 4; ++m) { const bf16_t* prow = P + (size_t)(row0 + ai * HALF + m * 16) * DP;
; #pragma unroll
;                 for (int bj = 0; bj < 2; ++bj) { const int c = col0 + bj * HALF;
;                     float ga[8], gb[8]; unpack8(__builtin_nontemporal_load((const u32x4*)(prow + C_MA + c)), ga); unpack8(*(const u32x4*)(prow + C_MB + c), gb);
; #pragma unroll
;                     for (int e = 0; e < 4; ++e) { acc[ai][bj][m][0][e] *= (1.0f + __expf(-gb[e])) * __builtin_amdgcn_rcpf(1.0f + __expf(-ga[e]));
;                                                   acc[ai][bj][m][1][e] *= (1.0f + __expf(-gb[4 + e])) * __builtin_amdgcn_rcpf(1.0f + __expf(-ga[4 + e])); } }
;                 asm volatile("" ::: "memory"); }
	v_lshlrev_b32_e32 v174, 16, v200
	v_lshlrev_b32_e32 v175, 16, v201
	v_lshlrev_b32_e32 v176, 16, v202
	v_lshlrev_b32_e32 v177, 16, v203
	v_and_b32_e32 v200, 0xffff0000, v200
	v_and_b32_e32 v201, 0xffff0000, v201
	v_and_b32_e32 v202, 0xffff0000, v202
	v_and_b32_e32 v203, 0xffff0000, v203
	v_lshlrev_b32_e32 v205, 16, v132
	v_lshlrev_b32_e32 v206, 16, v133
	v_lshlrev_b32_e32 v208, 16, v134
	v_lshlrev_b32_e32 v210, 16, v135
	v_and_b32_e32 v132, 0xffff0000, v132
	v_and_b32_e32 v133, 0xffff0000, v133
	v_and_b32_e32 v134, 0xffff0000, v134
	v_and_b32_e32 v135, 0xffff0000, v135
	v_mul_f32_e32 v174, 0xbfb8aa3b, v174
	v_mul_f32_e32 v200, 0xbfb8aa3b, v200
	v_mul_f32_e32 v175, 0xbfb8aa3b, v175
	v_mul_f32_e32 v201, 0xbfb8aa3b, v201
	v_mul_f32_e32 v176, 0xbfb8aa3b, v176
	v_mul_f32_e32 v202, 0xbfb8aa3b, v202
	v_mul_f32_e32 v177, 0xbfb8aa3b, v177
	v_mul_f32_e32 v203, 0xbfb8aa3b, v203
	v_mul_f32_e32 v205, 0xbfb8aa3b, v205
	v_mul_f32_e32 v132, 0xbfb8aa3b, v132
	v_mul_f32_e32 v206, 0xbfb8aa3b, v206
	v_mul_f32_e32 v133, 0xbfb8aa3b, v133
	v_mul_f32_e32 v208, 0xbfb8aa3b, v208
	v_mul_f32_e32 v134, 0xbfb8aa3b, v134
	v_mul_f32_e32 v210, 0xbfb8aa3b, v210
	v_mul_f32_e32 v135, 0xbfb8aa3b, v135
	v_exp_f32_e32 v174, v174
	v_exp_f32_e32 v200, v200
	v_exp_f32_e32 v175, v175
	v_exp_f32_e32 v201, v201
	v_exp_f32_e32 v176, v176
	v_exp_f32_e32 v202, v202
	v_exp_f32_e32 v177, v177
	v_exp_f32_e32 v203, v203
	v_exp_f32_e32 v205, v205
	v_exp_f32_e32 v132, v132
	v_exp_f32_e32 v206, v206
	v_exp_f32_e32 v133, v133
	v_exp_f32_e32 v208, v208
	v_exp_f32_e32 v134, v134
	v_exp_f32_e32 v210, v210
	v_exp_f32_e32 v135, v135
	v_add_f32_e32 v174, 1.0, v174
	v_add_f32_e32 v200, 1.0, v200
	v_add_f32_e32 v175, 1.0, v175
	v_add_f32_e32 v201, 1.0, v201
	v_add_f32_e32 v176, 1.0, v176
	v_add_f32_e32 v202, 1.0, v202
	v_add_f32_e32 v177, 1.0, v177
	v_add_f32_e32 v203, 1.0, v203
	v_add_f32_e32 v205, 1.0, v205
	v_add_f32_e32 v132, 1.0, v132
	v_add_f32_e32 v206, 1.0, v206
	v_add_f32_e32 v133, 1.0, v133
	v_add_f32_e32 v208, 1.0, v208
	v_add_f32_e32 v134, 1.0, v134
	v_add_f32_e32 v210, 1.0, v210
	v_add_f32_e32 v135, 1.0, v135
	v_rcp_f32_e32 v174, v174
	v_rcp_f32_e32 v200, v200
	v_rcp_f32_e32 v175, v175
	v_rcp_f32_e32 v201, v201
	v_rcp_f32_e32 v176, v176
	v_rcp_f32_e32 v202, v202
	v_rcp_f32_e32 v177, v177
	v_rcp_f32_e32 v203, v203
	v_mul_f32_e32 v205, v205, v174
	v_mul_f32_e32 v132, v132, v200
	v_mul_f32_e32 v206, v206, v175
	v_mul_f32_e32 v133, v133, v201
	v_mul_f32_e32 v208, v208, v176
	v_mul_f32_e32 v134, v134, v202
	v_mul_f32_e32 v210, v210, v177
	v_mul_f32_e32 v135, v135, v203
	v_mul_f32_e32 v16, v16, v205
	v_mul_f32_e32 v17, v17, v132
	v_mul_f32_e32 v18, v18, v206
	v_mul_f32_e32 v19, v19, v133
	v_mul_f32_e32 v12, v12, v208
	v_mul_f32_e32 v13, v13, v134
	v_mul_f32_e32 v14, v14, v210
	v_mul_f32_e32 v15, v15, v135
	s_waitcnt vmcnt(2)
;     __device__ __forceinline__ void mid(f32x4 (&acc)[2][2][4][2], const Unit& u, int wr, int wc, int fr, int fq) const {
;         const int row0 = u.pm * BM + wr * 64 + fr, col0 = u.pn * BM + wc * 32 + 8 * fq;
; #pragma unroll
;         for (int ai = 0; ai < 2; ++ai)
; #pragma unroll
;             for (int m = 0; m < 4; ++m) { const bf16_t* prow = P + (size_t)(row0 + ai * HALF + m * 16) * DP;
; #pragma unroll
;                 for (int bj = 0; bj < 2; ++bj) { const int c = col0 + bj * HALF;
;                     float ga[8], gb[8]; unpack8(__builtin_nontemporal_load((const u32x4*)(prow + C_MA + c)), ga); unpack8(*(const u32x4*)(prow + C_MB + c), gb);
; #pragma unroll
;                     for (int e = 0; e < 4; ++e) { acc[ai][bj][m][0][e] *= (1.0f + __expf(-gb[e])) * __builtin_amdgcn_rcpf(1.0f + __expf(-ga[e]));
;                                                   acc[ai][bj][m][1][e] *= (1.0f + __expf(-gb[4 + e])) * __builtin_amdgcn_rcpf(1.0f + __expf(-ga[4 + e])); } }
;                 asm volatile("" ::: "memory"); }
	v_lshlrev_b32_e32 v174, 16, v224
	v_lshlrev_b32_e32 v175, 16, v225
	v_lshlrev_b32_e32 v176, 16, v226
	v_lshlrev_b32_e32 v177, 16, v227
	v_and_b32_e32 v224, 0xffff0000, v224
	v_and_b32_e32 v225, 0xffff0000, v225
	v_and_b32_e32 v226, 0xffff0000, v226
	v_and_b32_e32 v227, 0xffff0000, v227
	v_lshlrev_b32_e32 v205, 16, v136
	v_lshlrev_b32_e32 v206, 16, v137
	v_lshlrev_b32_e32 v208, 16, v138
	v_lshlrev_b32_e32 v210, 16, v139
	v_and_b32_e32 v136, 0xffff0000, v136
	v_and_b32_e32 v137, 0xffff0000, v137
	v_and_b32_e32 v138, 0xffff0000, v138
	v_and_b32_e32 v139, 0xffff0000, v139
	v_mul_f32_e32 v174, 0xbfb8aa3b, v174
	v_mul_f32_e32 v224, 0xbfb8aa3b, v224
	v_mul_f32_e32 v175, 0xbfb8aa3b, v175
	v_mul_f32_e32 v225, 0xbfb8aa3b, v225
	v_mul_f32_e32 v176, 0xbfb8aa3b, v176
	v_mul_f32_e32 v226, 0xbfb8aa3b, v226
	v_mul_f32_e32 v177, 0xbfb8aa3b, v177
	v_mul_f32_e32 v227, 0xbfb8aa3b, v227
	v_mul_f32_e32 v205, 0xbfb8aa3b, v205
	v_mul_f32_e32 v136, 0xbfb8aa3b, v136
	v_mul_f32_e32 v206, 0xbfb8aa3b, v206
	v_mul_f32_e32 v137, 0xbfb8aa3b, v137
	v_mul_f32_e32 v208, 0xbfb8aa3b, v208
	v_mul_f32_e32 v138, 0xbfb8aa3b, v138
	v_mul_f32_e32 v210, 0xbfb8aa3b, v210
	v_mul_f32_e32 v139, 0xbfb8aa3b, v139
	v_exp_f32_e32 v174, v174
	v_exp_f32_e32 v224, v224
	v_exp_f32_e32 v175, v175
	v_exp_f32_e32 v225, v225
	v_exp_f32_e32 v176, v176
	v_exp_f32_e32 v226, v226
	v_exp_f32_e32 v177, v177
	v_exp_f32_e32 v227, v227
	v_exp_f32_e32 v205, v205
	v_exp_f32_e32 v136, v136
	v_exp_f32_e32 v206, v206
	v_exp_f32_e32 v137, v137
	v_exp_f32_e32 v208, v208
	v_exp_f32_e32 v138, v138
	v_exp_f32_e32 v210, v210
	v_exp_f32_e32 v139, v139
	v_add_f32_e32 v174, 1.0, v174
	v_add_f32_e32 v224, 1.0, v224
	v_add_f32_e32 v175, 1.0, v175
	v_add_f32_e32 v225, 1.0, v225
	v_add_f32_e32 v176, 1.0, v176
	v_add_f32_e32 v226, 1.0, v226
	v_add_f32_e32 v177, 1.0, v177
	v_add_f32_e32 v227, 1.0, v227
	v_add_f32_e32 v205, 1.0, v205
	v_add_f32_e32 v136, 1.0, v136
	v_add_f32_e32 v206, 1.0, v206
	v_add_f32_e32 v137, 1.0, v137
	v_add_f32_e32 v208, 1.0, v208
	v_add_f32_e32 v138, 1.0, v138
	v_add_f32_e32 v210, 1.0, v210
	v_add_f32_e32 v139, 1.0, v139
	v_rcp_f32_e32 v174, v174
	v_rcp_f32_e32 v224, v224
	v_rcp_f32_e32 v175, v175
	v_rcp_f32_e32 v225, v225
	v_rcp_f32_e32 v176, v176
	v_rcp_f32_e32 v226, v226
	v_rcp_f32_e32 v177, v177
	v_rcp_f32_e32 v227, v227
	v_mul_f32_e32 v205, v205, v174
	v_mul_f32_e32 v136, v136, v224
	v_mul_f32_e32 v206, v206, v175
	v_mul_f32_e32 v137, v137, v225
	v_mul_f32_e32 v208, v208, v176
	v_mul_f32_e32 v138, v138, v226
	v_mul_f32_e32 v210, v210, v177
	v_mul_f32_e32 v139, v139, v227
	v_mul_f32_e32 v40, v40, v205
	v_mul_f32_e32 v41, v41, v136
	v_mul_f32_e32 v42, v42, v206
	v_mul_f32_e32 v43, v43, v137
	v_mul_f32_e32 v36, v36, v208
	v_mul_f32_e32 v37, v37, v138
	v_mul_f32_e32 v38, v38, v210
	v_mul_f32_e32 v39, v39, v139
	s_waitcnt vmcnt(0)
	v_lshlrev_b32_e32 v174, 16, v228
	v_lshlrev_b32_e32 v175, 16, v229
	v_lshlrev_b32_e32 v176, 16, v230
	v_lshlrev_b32_e32 v177, 16, v231
	v_and_b32_e32 v228, 0xffff0000, v228
	v_and_b32_e32 v229, 0xffff0000, v229
	v_and_b32_e32 v230, 0xffff0000, v230
	v_and_b32_e32 v231, 0xffff0000, v231
	v_lshlrev_b32_e32 v205, 16, v170
	v_lshlrev_b32_e32 v206, 16, v171
	v_lshlrev_b32_e32 v208, 16, v172
	v_lshlrev_b32_e32 v210, 16, v173
	v_and_b32_e32 v170, 0xffff0000, v170
	v_and_b32_e32 v171, 0xffff0000, v171
	v_and_b32_e32 v172, 0xffff0000, v172
	v_and_b32_e32 v173, 0xffff0000, v173
	v_mul_f32_e32 v174, 0xbfb8aa3b, v174
	v_mul_f32_e32 v228, 0xbfb8aa3b, v228
	v_mul_f32_e32 v175, 0xbfb8aa3b, v175
	v_mul_f32_e32 v229, 0xbfb8aa3b, v229
	v_mul_f32_e32 v176, 0xbfb8aa3b, v176
	v_mul_f32_e32 v230, 0xbfb8aa3b, v230
	v_mul_f32_e32 v177, 0xbfb8aa3b, v177
	v_mul_f32_e32 v231, 0xbfb8aa3b, v231
	v_mul_f32_e32 v205, 0xbfb8aa3b, v205
	v_mul_f32_e32 v170, 0xbfb8aa3b, v170
	v_mul_f32_e32 v206, 0xbfb8aa3b, v206
	v_mul_f32_e32 v171, 0xbfb8aa3b, v171
	v_mul_f32_e32 v208, 0xbfb8aa3b, v208
	v_mul_f32_e32 v172, 0xbfb8aa3b, v172
	v_mul_f32_e32 v210, 0xbfb8aa3b, v210
	v_mul_f32_e32 v173, 0xbfb8aa3b, v173
	v_exp_f32_e32 v174, v174
	v_exp_f32_e32 v228, v228
	v_exp_f32_e32 v175, v175
	v_exp_f32_e32 v229, v229
	v_exp_f32_e32 v176, v176
	v_exp_f32_e32 v230, v230
	v_exp_f32_e32 v177, v177
	v_exp_f32_e32 v231, v231
	v_exp_f32_e32 v205, v205
	v_exp_f32_e32 v170, v170
	v_exp_f32_e32 v206, v206
	v_exp_f32_e32 v171, v171
	v_exp_f32_e32 v208, v208
	v_exp_f32_e32 v172, v172
	v_exp_f32_e32 v210, v210
	v_exp_f32_e32 v173, v173
	v_add_f32_e32 v174, 1.0, v174
	v_add_f32_e32 v228, 1.0, v228
	v_add_f32_e32 v175, 1.0, v175
	v_add_f32_e32 v229, 1.0, v229
	v_add_f32_e32 v176, 1.0, v176
	v_add_f32_e32 v230, 1.0, v230
	v_add_f32_e32 v177, 1.0, v177
	v_add_f32_e32 v231, 1.0, v231
	v_add_f32_e32 v205, 1.0, v205
	v_add_f32_e32 v170, 1.0, v170
	v_add_f32_e32 v206, 1.0, v206
	v_add_f32_e32 v171, 1.0, v171
	v_add_f32_e32 v208, 1.0, v208
	v_add_f32_e32 v172, 1.0, v172
	v_add_f32_e32 v210, 1.0, v210
	v_add_f32_e32 v173, 1.0, v173
	v_rcp_f32_e32 v174, v174
	v_rcp_f32_e32 v228, v228
	v_rcp_f32_e32 v175, v175
	v_rcp_f32_e32 v229, v229
	v_rcp_f32_e32 v176, v176
	v_rcp_f32_e32 v230, v230
	v_rcp_f32_e32 v177, v177
	v_rcp_f32_e32 v231, v231
	v_mul_f32_e32 v205, v205, v174
	v_mul_f32_e32 v170, v170, v228
	v_mul_f32_e32 v206, v206, v175
	v_mul_f32_e32 v171, v171, v229
	v_mul_f32_e32 v208, v208, v176
	v_mul_f32_e32 v172, v172, v230
	v_mul_f32_e32 v210, v210, v177
	v_mul_f32_e32 v173, v173, v231
	v_mul_f32_e32 v8, v8, v205
	v_mul_f32_e32 v9, v9, v170
	v_mul_f32_e32 v10, v10, v206
	v_mul_f32_e32 v11, v11, v171
	v_mul_f32_e32 v4, v4, v208
	v_mul_f32_e32 v5, v5, v172
	v_mul_f32_e32 v6, v6, v210
	v_mul_f32_e32 v7, v7, v173
	s_branch .LBB0_579

; __device__ __forceinline__ int tid_() { int t = threadIdx.x; asm volatile("" : "+v"(t)); return t; }
; __device__ __forceinline__ int bid_() { int t = blockIdx.x; asm volatile("" : "+s"(t)); return t; }
; __device__ __forceinline__ int gdim_() { int t = gridDim.x; asm volatile("" : "+s"(t)); return t; }
; __device__ __forceinline__ void ffn_edge_phase(KP p, int l) {
;     bf16_t* ACT = (bf16_t*)(p->ws + WS_BIG); const bf16_t* EF = (const bf16_t*)(p->ws + WS_SLAB); const bf16_t* EL = EF + (size_t)260 * 2 * 2 * DFF;
;     const int gt = bid_() * 512 + tid_(), NT = gdim_() * 512;
;     constexpr int NCG = DFF / 8, NIT = 258 * 2 * NCG;
;     const float* cw = p->in[25] + (size_t)l * 3 * DFF; const float* cb = p->in[26] + (size_t)l * DFF;
;     for (int it = gt; it < NIT; it += NT) {
;         const int rq = it / NCG, c0 = (it - rq * NCG) * 8, q = rq & 1, blk = rq >> 1, r = 64 * blk + q, b = r / TP, t = r - b * TP;
;         float w0[8], w1[8], w2[8], bb[8]; load8f(cw + c0, w0); load8f(cw + DFF + c0, w1); load8f(cw + 2 * DFF + c0, w2); load8f(cb + c0, bb);
;         float u0[8], g0[8], u1[8], u2[8], o[8];
;         unpack8(*(const u32x4*)(EF + ((size_t)(blk * 2 + q) * 2) * DFF + c0), u0); unpack8(*(const u32x4*)(EF + ((size_t)(blk * 2 + q) * 2 + 1) * DFF + c0), g0);
; #pragma unroll
;         for (int e = 0; e < 8; ++e) { u1[e] = 0.f; u2[e] = 0.f; }
;         if (t >= 1) { if (q == 1) unpack8(*(const u32x4*)(EF + ((size_t)(blk * 2) * 2) * DFF + c0), u1); else unpack8(*(const u32x4*)(EL + (size_t)((blk - 1) * 2 + 1) * DFF + c0), u1); }
;         if (t >= 2) { if (q == 1) unpack8(*(const u32x4*)(EL + (size_t)((blk - 1) * 2 + 1) * DFF + c0), u2); else unpack8(*(const u32x4*)(EL + (size_t)((blk - 1) * 2) * DFF + c0), u2); }
.LBB0_1008:
	s_or_b64 exec, exec, s[4:5]
	s_mov_b64 s[6:7], s[0:1]
	s_mov_b32 s4, s2
	v_mov_b32_e32 v0, v209
	s_waitcnt lgkmcnt(0)
	s_barrier
	s_mov_b64 s[4:5], exec
	s_load_dwordx2 s[8:9], s[6:7], 0xe8
	s_load_dwordx2 s[70:71], s[6:7], 0xc8
	s_load_dwordx2 s[72:73], s[6:7], 0xd0
	s_add_i32 s10, s86, -1
	s_mul_i32 s16, s10, 0x8400
	s_mul_i32 s21, s10, 0x2c00
	v_lshl_add_u32 v18, s2, 9, v0
	v_add_u32_e32 v96, 0x20000, v18
	v_min_u32_e32 v96, 0x2c57f, v96
	s_waitcnt lgkmcnt(0)
	s_add_u32 s12, s8, 0x1a3ac000
	s_addc_u32 s13, s9, 0
	s_add_u32 s18, s8, 0x66c8000
	s_addc_u32 s19, s9, 0
	s_add_u32 s24, s70, s16
	s_addc_u32 s25, s71, 0
	s_add_u32 s34, s72, s21
	s_addc_u32 s35, s73, 0
	v_lshrrev_b32_e32 v19, 5, v18
	v_mov_b32_e32 v32, 0x1745d175
	v_mul_hi_u32 v20, v19, v32
	v_mul_u32_u24_e32 v21, 0x160, v20
	v_sub_u32_e32 v21, v18, v21
	v_lshlrev_b32_e32 v22, 4, v21
	v_lshlrev_b32_e32 v23, 5, v21
	v_and_b32_e32 v24, 1, v20
	v_lshrrev_b32_e32 v25, 1, v20
	v_lshl_or_b32 v26, v25, 6, v24
	v_lshrrev_b32_e32 v19, 4, v26
	v_mov_b32_e32 v32, 0x1fc07f1
	v_mul_hi_u32 v19, v19, v32
	v_mul_u32_u24_e32 v19, 0x810, v19
	v_sub_u32_e32 v27, v26, v19
	v_mov_b32_e32 v32, 0x2c00
	v_mad_u32_u24 v28, v20, v32, v22
	v_subrev_u32_e32 v19, 0x2c00, v28
	v_subrev_u32_e32 v25, 1, v25
	v_max_i32_e32 v25, 0, v25
	v_mad_u32_u24 v30, v25, v32, v22
	v_add_u32_e32 v30, 0x596000, v30
	v_add_u32_e32 v29, 0x1600, v30
	v_cmp_eq_u32_e32 vcc, 1, v24
	s_nop 1
	v_cndmask_b32_e32 v30, v30, v29, vcc
	v_cndmask_b32_e32 v29, v29, v19, vcc
	v_mov_b32_e32 v32, 0x1600
	v_mad_u32_u24 v31, v26, v32, v22
	v_lshrrev_b32_e32 v97, 5, v96
	v_mov_b32_e32 v110, 0x1745d175
	v_mul_hi_u32 v98, v97, v110
	v_mul_u32_u24_e32 v99, 0x160, v98
	v_sub_u32_e32 v99, v96, v99
	v_lshlrev_b32_e32 v100, 4, v99
	v_lshlrev_b32_e32 v101, 5, v99
	v_and_b32_e32 v102, 1, v98
	v_lshrrev_b32_e32 v103, 1, v98
	v_lshl_or_b32 v104, v103, 6, v102
	v_lshrrev_b32_e32 v97, 4, v104
	v_mov_b32_e32 v110, 0x1fc07f1
	v_mul_hi_u32 v97, v97, v110
	v_mul_u32_u24_e32 v97, 0x810, v97
	v_sub_u32_e32 v105, v104, v97
	v_mov_b32_e32 v110, 0x2c00
	v_mad_u32_u24 v106, v98, v110, v100
	v_subrev_u32_e32 v97, 0x2c00, v106
	v_subrev_u32_e32 v103, 1, v103
	v_max_i32_e32 v103, 0, v103
	v_mad_u32_u24 v108, v103, v110, v100
	v_add_u32_e32 v108, 0x596000, v108
	v_add_u32_e32 v107, 0x1600, v108
	v_cmp_eq_u32_e32 vcc, 1, v102
	s_nop 1
	v_cndmask_b32_e32 v108, v108, v107, vcc
	v_cndmask_b32_e32 v107, v107, v97, vcc
	v_mov_b32_e32 v110, 0x1600
	v_mad_u32_u24 v109, v104, v110, v100
	global_load_dwordx4 v[36:39], v23, s[24:25]
	global_load_dwordx4 v[40:43], v23, s[24:25] offset:16
	v_add_u32_e32 v32, 0x2c00, v23
	global_load_dwordx4 v[44:47], v32, s[24:25]
	global_load_dwordx4 v[48:51], v32, s[24:25] offset:16
	v_add_u32_e32 v32, 0x5800, v23
	global_load_dwordx4 v[52:55], v32, s[24:25]
	global_load_dwordx4 v[56:59], v32, s[24:25] offset:16
	global_load_dwordx4 v[60:63], v23, s[34:35]
	global_load_dwordx4 v[64:67], v23, s[34:35] offset:16
	global_load_dwordx4 v[68:71], v28, s[12:13]
	v_add_u32_e32 v32, 0x1600, v28
	global_load_dwordx4 v[72:75], v32, s[12:13]
	global_load_dwordx4 v[76:79], v29, s[12:13]
	global_load_dwordx4 v[80:83], v30, s[12:13]
	global_load_dwordx4 v[112:115], v101, s[24:25]
	global_load_dwordx4 v[116:119], v101, s[24:25] offset:16
	v_add_u32_e32 v110, 0x2c00, v101
	global_load_dwordx4 v[120:123], v110, s[24:25]
	global_load_dwordx4 v[124:127], v110, s[24:25] offset:16
	v_add_u32_e32 v110, 0x5800, v101
	global_load_dwordx4 v[128:131], v110, s[24:25]
	global_load_dwordx4 v[132:135], v110, s[24:25] offset:16
	global_load_dwordx4 v[136:139], v101, s[34:35]
	global_load_dwordx4 v[140:143], v101, s[34:35] offset:16
	global_load_dwordx4 v[144:147], v106, s[12:13]
	v_add_u32_e32 v110, 0x1600, v106
	global_load_dwordx4 v[148:151], v110, s[12:13]
	global_load_dwordx4 v[152:155], v107, s[12:13]
	global_load_dwordx4 v[156:159], v108, s[12:13]
	s_waitcnt vmcnt(0)
	v_lshlrev_b32_e32 v160, 16, v68
	v_and_b32_e32 v161, 0xffff0000, v68
	v_lshlrev_b32_e32 v162, 16, v69
	v_and_b32_e32 v163, 0xffff0000, v69
	v_lshlrev_b32_e32 v164, 16, v70
	v_and_b32_e32 v165, 0xffff0000, v70
	v_lshlrev_b32_e32 v166, 16, v71
	v_and_b32_e32 v167, 0xffff0000, v71
	v_lshlrev_b32_e32 v168, 16, v72
	v_and_b32_e32 v169, 0xffff0000, v72
	v_lshlrev_b32_e32 v170, 16, v73
	v_and_b32_e32 v171, 0xffff0000, v73
	v_lshlrev_b32_e32 v172, 16, v74
	v_and_b32_e32 v173, 0xffff0000, v74
	v_lshlrev_b32_e32 v174, 16, v75
	v_and_b32_e32 v175, 0xffff0000, v75
	v_lshlrev_b32_e32 v176, 16, v76
	v_and_b32_e32 v177, 0xffff0000, v76
	v_lshlrev_b32_e32 v178, 16, v77
	v_and_b32_e32 v179, 0xffff0000, v77
	v_lshlrev_b32_e32 v180, 16, v78
	v_and_b32_e32 v181, 0xffff0000, v78
	v_lshlrev_b32_e32 v182, 16, v79
	v_and_b32_e32 v183, 0xffff0000, v79
	v_lshlrev_b32_e32 v184, 16, v80
	v_and_b32_e32 v185, 0xffff0000, v80
	v_lshlrev_b32_e32 v186, 16, v81
	v_and_b32_e32 v187, 0xffff0000, v81
	v_lshlrev_b32_e32 v188, 16, v82
	v_and_b32_e32 v189, 0xffff0000, v82
	v_lshlrev_b32_e32 v190, 16, v83
	v_and_b32_e32 v191, 0xffff0000, v83
	v_cmp_lt_u32_e32 vcc, 0, v27
	s_nop 1
	v_cndmask_b32_e32 v176, 0, v176, vcc
	v_cndmask_b32_e32 v177, 0, v177, vcc
	v_cndmask_b32_e32 v178, 0, v178, vcc
	v_cndmask_b32_e32 v179, 0, v179, vcc
	v_cndmask_b32_e32 v180, 0, v180, vcc
	v_cndmask_b32_e32 v181, 0, v181, vcc
	v_cndmask_b32_e32 v182, 0, v182, vcc
	v_cndmask_b32_e32 v183, 0, v183, vcc
	v_cmp_lt_u32_e32 vcc, 1, v27
	s_nop 1
	v_cndmask_b32_e32 v184, 0, v184, vcc
	v_cndmask_b32_e32 v185, 0, v185, vcc
	v_cndmask_b32_e32 v186, 0, v186, vcc
	v_cndmask_b32_e32 v187, 0, v187, vcc
	v_cndmask_b32_e32 v188, 0, v188, vcc
	v_cndmask_b32_e32 v189, 0, v189, vcc
; __device__ __forceinline__ u32x4 pack8(const float (&f)[8]) { u32x4 o; o.x = cvt_pk_bf16(f[0], f[1]); o.y = cvt_pk_bf16(f[2], f[3]); o.z = cvt_pk_bf16(f[4], f[5]); o.w = cvt_pk_bf16(f[6], f[7]); return o; }
; __device__ __forceinline__ float sigmoidf_(float x) { return __builtin_amdgcn_rcpf(1.0f + __expf(-x)); }
; __device__ __forceinline__ void ffn_edge_phase(KP p, int l) {
;     ...
; #pragma unroll
;         for (int e = 0; e < 8; ++e) { const float uc = w0[e] * u2[e] + w1[e] * u1[e] + w2[e] * u0[e] + bb[e]; o[e] = uc * sigmoidf_(uc) * g0[e]; }
;         *(u32x4*)(ACT + (size_t)r * DFF + c0) = pack8(o);
	v_cndmask_b32_e32 v190, 0, v190, vcc
	v_cndmask_b32_e32 v191, 0, v191, vcc
	v_fma_f32 v160, v52, v160, v60
	v_fma_f32 v161, v53, v161, v61
	v_fma_f32 v162, v54, v162, v62
	v_fma_f32 v163, v55, v163, v63
	v_fma_f32 v164, v56, v164, v64
	v_fma_f32 v165, v57, v165, v65
	v_fma_f32 v166, v58, v166, v66
	v_fma_f32 v167, v59, v167, v67
	v_fmac_f32_e32 v160, v44, v176
	v_fmac_f32_e32 v161, v45, v177
	v_fmac_f32_e32 v162, v46, v178
	v_fmac_f32_e32 v163, v47, v179
	v_fmac_f32_e32 v164, v48, v180
	v_fmac_f32_e32 v165, v49, v181
	v_fmac_f32_e32 v166, v50, v182
	v_fmac_f32_e32 v167, v51, v183
	v_fmac_f32_e32 v160, v36, v184
	v_fmac_f32_e32 v161, v37, v185
	v_fmac_f32_e32 v162, v38, v186
	v_fmac_f32_e32 v163, v39, v187
	v_fmac_f32_e32 v164, v40, v188
	v_fmac_f32_e32 v165, v41, v189
	v_fmac_f32_e32 v166, v42, v190
	v_fmac_f32_e32 v167, v43, v191
	v_mul_f32_e32 v192, 0xbfb8aa3b, v160
	v_mul_f32_e32 v193, 0xbfb8aa3b, v161
	v_mul_f32_e32 v194, 0xbfb8aa3b, v162
	v_mul_f32_e32 v195, 0xbfb8aa3b, v163
	v_mul_f32_e32 v196, 0xbfb8aa3b, v164
	v_mul_f32_e32 v197, 0xbfb8aa3b, v165
	v_mul_f32_e32 v198, 0xbfb8aa3b, v166
	v_mul_f32_e32 v199, 0xbfb8aa3b, v167
	v_exp_f32_e32 v192, v192
	v_exp_f32_e32 v193, v193
	v_exp_f32_e32 v194, v194
	v_exp_f32_e32 v195, v195
	v_exp_f32_e32 v196, v196
	v_exp_f32_e32 v197, v197
	v_exp_f32_e32 v198, v198
	v_exp_f32_e32 v199, v199
	v_add_f32_e32 v192, 1.0, v192
	v_add_f32_e32 v193, 1.0, v193
	v_add_f32_e32 v194, 1.0, v194
	v_add_f32_e32 v195, 1.0, v195
	v_add_f32_e32 v196, 1.0, v196
	v_add_f32_e32 v197, 1.0, v197
	v_add_f32_e32 v198, 1.0, v198
	v_add_f32_e32 v199, 1.0, v199
	v_rcp_f32_e32 v192, v192
	v_rcp_f32_e32 v193, v193
	v_rcp_f32_e32 v194, v194
	v_rcp_f32_e32 v195, v195
	v_rcp_f32_e32 v196, v196
	v_rcp_f32_e32 v197, v197
	v_rcp_f32_e32 v198, v198
	v_rcp_f32_e32 v199, v199
	v_mul_f32_e32 v160, v160, v192
	v_mul_f32_e32 v161, v161, v193
	v_mul_f32_e32 v162, v162, v194
	v_mul_f32_e32 v163, v163, v195
	v_mul_f32_e32 v164, v164, v196
	v_mul_f32_e32 v165, v165, v197
	v_mul_f32_e32 v166, v166, v198
	v_mul_f32_e32 v167, v167, v199
	v_mul_f32_e32 v160, v160, v168
	v_mul_f32_e32 v161, v161, v169
	v_mul_f32_e32 v162, v162, v170
	v_mul_f32_e32 v163, v163, v171
	v_mul_f32_e32 v164, v164, v172
	v_mul_f32_e32 v165, v165, v173
	v_mul_f32_e32 v166, v166, v174
	v_mul_f32_e32 v167, v167, v175
	v_cvt_pk_bf16_f32 v200, v160, v161
	v_cvt_pk_bf16_f32 v201, v162, v163
	v_cvt_pk_bf16_f32 v202, v164, v165
	v_cvt_pk_bf16_f32 v203, v166, v167
	global_store_dwordx4 v31, v[200:203], s[18:19]
	v_lshlrev_b32_e32 v160, 16, v144
	v_and_b32_e32 v161, 0xffff0000, v144
	v_lshlrev_b32_e32 v162, 16, v145
	v_and_b32_e32 v163, 0xffff0000, v145
	v_lshlrev_b32_e32 v164, 16, v146
	v_and_b32_e32 v165, 0xffff0000, v146
	v_lshlrev_b32_e32 v166, 16, v147
	v_and_b32_e32 v167, 0xffff0000, v147
	v_lshlrev_b32_e32 v168, 16, v148
	v_and_b32_e32 v169, 0xffff0000, v148
	v_lshlrev_b32_e32 v170, 16, v149
	v_and_b32_e32 v171, 0xffff0000, v149
	v_lshlrev_b32_e32 v172, 16, v150
	v_and_b32_e32 v173, 0xffff0000, v150
	v_lshlrev_b32_e32 v174, 16, v151
	v_and_b32_e32 v175, 0xffff0000, v151
	v_lshlrev_b32_e32 v176, 16, v152
	v_and_b32_e32 v177, 0xffff0000, v152
	v_lshlrev_b32_e32 v178, 16, v153
	v_and_b32_e32 v179, 0xffff0000, v153
	v_lshlrev_b32_e32 v180, 16, v154
	v_and_b32_e32 v181, 0xffff0000, v154
	v_lshlrev_b32_e32 v182, 16, v155
	v_and_b32_e32 v183, 0xffff0000, v155
	v_lshlrev_b32_e32 v184, 16, v156
	v_and_b32_e32 v185, 0xffff0000, v156
	v_lshlrev_b32_e32 v186, 16, v157
	v_and_b32_e32 v187, 0xffff0000, v157
	v_lshlrev_b32_e32 v188, 16, v158
	v_and_b32_e32 v189, 0xffff0000, v158
	v_lshlrev_b32_e32 v190, 16, v159
	v_and_b32_e32 v191, 0xffff0000, v159
	v_cmp_lt_u32_e32 vcc, 0, v105
	s_nop 1
	v_cndmask_b32_e32 v176, 0, v176, vcc
	v_cndmask_b32_e32 v177, 0, v177, vcc
	v_cndmask_b32_e32 v178, 0, v178, vcc
	v_cndmask_b32_e32 v179, 0, v179, vcc
	v_cndmask_b32_e32 v180, 0, v180, vcc
	v_cndmask_b32_e32 v181, 0, v181, vcc
	v_cndmask_b32_e32 v182, 0, v182, vcc
	v_cndmask_b32_e32 v183, 0, v183, vcc
	v_cmp_lt_u32_e32 vcc, 1, v105
	s_nop 1
	v_cndmask_b32_e32 v184, 0, v184, vcc
	v_cndmask_b32_e32 v185, 0, v185, vcc
	v_cndmask_b32_e32 v186, 0, v186, vcc
	v_cndmask_b32_e32 v187, 0, v187, vcc
	v_cndmask_b32_e32 v188, 0, v188, vcc
	v_cndmask_b32_e32 v189, 0, v189, vcc
	v_cndmask_b32_e32 v190, 0, v190, vcc
	v_cndmask_b32_e32 v191, 0, v191, vcc
	v_fma_f32 v160, v128, v160, v136
	v_fma_f32 v161, v129, v161, v137
	v_fma_f32 v162, v130, v162, v138
	v_fma_f32 v163, v131, v163, v139
	v_fma_f32 v164, v132, v164, v140
	v_fma_f32 v165, v133, v165, v141
	v_fma_f32 v166, v134, v166, v142
	v_fma_f32 v167, v135, v167, v143
	v_fmac_f32_e32 v160, v120, v176
	v_fmac_f32_e32 v161, v121, v177
	v_fmac_f32_e32 v162, v122, v178
	v_fmac_f32_e32 v163, v123, v179
	v_fmac_f32_e32 v164, v124, v180
	v_fmac_f32_e32 v165, v125, v181
	v_fmac_f32_e32 v166, v126, v182
	v_fmac_f32_e32 v167, v127, v183
	v_fmac_f32_e32 v160, v112, v184
	v_fmac_f32_e32 v161, v113, v185
	v_fmac_f32_e32 v162, v114, v186
	v_fmac_f32_e32 v163, v115, v187
	v_fmac_f32_e32 v164, v116, v188
	v_fmac_f32_e32 v165, v117, v189
	v_fmac_f32_e32 v166, v118, v190
	v_fmac_f32_e32 v167, v119, v191
	v_mul_f32_e32 v192, 0xbfb8aa3b, v160
	v_mul_f32_e32 v193, 0xbfb8aa3b, v161
	v_mul_f32_e32 v194, 0xbfb8aa3b, v162
	v_mul_f32_e32 v195, 0xbfb8aa3b, v163
	v_mul_f32_e32 v196, 0xbfb8aa3b, v164
	v_mul_f32_e32 v197, 0xbfb8aa3b, v165
	v_mul_f32_e32 v198, 0xbfb8aa3b, v166
	v_mul_f32_e32 v199, 0xbfb8aa3b, v167
	v_exp_f32_e32 v192, v192
	v_exp_f32_e32 v193, v193
	v_exp_f32_e32 v194, v194
	v_exp_f32_e32 v195, v195
	v_exp_f32_e32 v196, v196
	v_exp_f32_e32 v197, v197
	v_exp_f32_e32 v198, v198
	v_exp_f32_e32 v199, v199
	v_add_f32_e32 v192, 1.0, v192
	v_add_f32_e32 v193, 1.0, v193
	v_add_f32_e32 v194, 1.0, v194
	v_add_f32_e32 v195, 1.0, v195
	v_add_f32_e32 v196, 1.0, v196
	v_add_f32_e32 v197, 1.0, v197
	v_add_f32_e32 v198, 1.0, v198
	v_add_f32_e32 v199, 1.0, v199
	v_rcp_f32_e32 v192, v192
	v_rcp_f32_e32 v193, v193
	v_rcp_f32_e32 v194, v194
	v_rcp_f32_e32 v195, v195
	v_rcp_f32_e32 v196, v196
	v_rcp_f32_e32 v197, v197
	v_rcp_f32_e32 v198, v198
	v_rcp_f32_e32 v199, v199
	v_mul_f32_e32 v160, v160, v192
	v_mul_f32_e32 v161, v161, v193
	v_mul_f32_e32 v162, v162, v194
	v_mul_f32_e32 v163, v163, v195
	v_mul_f32_e32 v164, v164, v196
	v_mul_f32_e32 v165, v165, v197
	v_mul_f32_e32 v166, v166, v198
	v_mul_f32_e32 v167, v167, v199
	v_mul_f32_e32 v160, v160, v168
	v_mul_f32_e32 v161, v161, v169
	v_mul_f32_e32 v162, v162, v170
	v_mul_f32_e32 v163, v163, v171
	v_mul_f32_e32 v164, v164, v172
	v_mul_f32_e32 v165, v165, v173
	v_mul_f32_e32 v166, v166, v174
	v_mul_f32_e32 v167, v167, v175
	v_cvt_pk_bf16_f32 v200, v160, v161
	v_cvt_pk_bf16_f32 v201, v162, v163
	v_cvt_pk_bf16_f32 v202, v164, v165
	v_cvt_pk_bf16_f32 v203, v166, v167
	v_cmp_gt_u32_e32 vcc, 0xc580, v18
	s_and_saveexec_b64 s[56:57], vcc
	global_store_dwordx4 v109, v[200:203], s[18:19]
	s_mov_b64 exec, s[56:57]
